# rwkv_scalars (phase 5) fused into the RWKV prep waves: per-head reductions + bonus*v store there; phase 5 and one grid seam removed
# speedup vs baseline: 1.0119x; 1.0012x over previous
.LBB0_1099:
.LBB0_1100:
	s_cmp_lt_i32 s50, 6
	s_cselect_b64 s[0:1], -1, 0
	s_and_b64 s[10:11], s[0:1], s[4:5]
	s_andn2_b64 vcc, exec, s[10:11]
	s_branch .LBB0_1222
	s_add_i32 s0, 0, 0x20020
	v_mov_b32_e32 v1, s0
	ds_read_b64 v[2:3], v1
	v_lshl_add_u32 v131, s2, 3, v179
	s_movk_i32 s0, 0x800
	v_cmp_gt_i32_e32 vcc, s0, v131
	s_waitcnt lgkmcnt(0)
	v_readfirstlane_b32 s12, v2
	v_readfirstlane_b32 s13, v3
	s_and_saveexec_b64 s[14:15], vcc
	s_cbranch_execz .LBB0_1221
	v_and_b32_e32 v1, 63, v178
	v_lshlrev_b32_e32 v1, 3, v1
	v_and_b32_e32 v2, 7, v178
	v_and_b32_e32 v3, 1, v179
	v_cmp_ne_u32_e64 s[4:5], 0, v2
	v_lshl_or_b32 v2, v3, 9, v1
	s_waitcnt vmcnt(0)
	v_mov_b32_e32 v123, 0
	v_lshlrev_b32_e32 v1, 1, v178
	v_lshlrev_b32_e32 v124, 1, v2
	v_mov_b32_e32 v125, v123
	v_and_b32_e32 v1, 0x7c, v1
	v_lshl_add_u64 v[4:5], s[46:47], 0, v[124:125]
	s_mov_b64 s[0:1], 0x1bb00000
	v_lshl_or_b32 v122, v3, 7, v1
	s_add_u32 s16, s46, 0x5200000
	v_lshl_add_u64 v[126:127], v[4:5], 0, s[0:1]
	v_lshl_add_u64 v[4:5], s[46:47], 0, v[122:123]
	s_mov_b64 s[0:1], 0x1b200000
	s_addc_u32 s17, s47, 0
	v_lshl_add_u64 v[128:129], v[4:5], 0, s[0:1]
	s_add_i32 s0, 0, 0x20080
	v_mov_b32_e32 v1, s0
	s_add_i32 s0, 0, 0x200b0
	v_mov_b32_e32 v3, s0
	s_add_i32 s0, 0, 0x200c0
	ds_read_b64 v[144:145], v1
	ds_read_b128 v[38:41], v3
	v_mov_b32_e32 v1, s0
	ds_read_b64 v[146:147], v1
	v_lshlrev_b32_e32 v152, 2, v2
	s_lshl_b32 s3, s48, 3
	v_or_b32_e32 v130, 1, v2
	v_or_b32_e32 v132, 2, v2
	v_or_b32_e32 v134, 3, v2
	v_or_b32_e32 v136, 4, v2
	v_or_b32_e32 v138, 5, v2
	v_or_b32_e32 v140, 6, v2
	v_or_b32_e32 v142, 7, v2
	v_or_b32_e32 v148, 0x1b200000, v122
	v_mov_b32_e32 v149, v123
	v_or_b32_e32 v150, 0x1bb00800, v124
	v_mov_b32_e32 v151, v123
	s_mov_b64 s[18:19], 0
	s_movk_i32 s34, 0x5200
	s_mov_b64 s[20:21], 0x2800
	s_movk_i32 s35, 0x3fff
	s_movk_i32 s36, 0x4000
	s_movk_i32 s37, 0x7ff
	s_movk_i32 s38, 0x3400
	s_mov_b64 s[22:23], 0x1000
	s_mov_b64 s[24:25], 0x2000
	s_mov_b32 s39, 0xf800000
	v_mov_b32_e32 v133, 0x260
	s_mov_b64 s[26:27], 0x5200
	s_mov_b64 s[28:29], 0x100
	s_mov_b64 s[30:31], 0x800
	s_movk_i32 s40, 0x3c2
	s_movk_i32 s41, 0x3c3
	v_mov_b32_e32 v154, v152
	v_mov_b32_e32 v155, v123
	v_mov_b64_e32 v[156:157], s[16:17]
	v_lshlrev_b32_e32 v122, 1, v2
	v_mov_b32_e32 v135, 0x7ff
	s_branch .LBB0_1104

.LBB0_1222:
	s_cmp_gt_i32 s51, 6
	s_cselect_b64 s[4:5], -1, 0
	s_and_b64 s[0:1], s[10:11], s[4:5]
	s_andn2_b64 vcc, exec, s[0:1]
	s_branch .LBB0_1290
	s_cmp_gt_i32 s50, -1
	s_mov_b64 s[6:7], -1
	s_cbranch_scc0 .LBB0_1277
	s_waitcnt vmcnt(0)
	s_waitcnt vmcnt(0)
	s_barrier
	s_and_saveexec_b64 s[6:7], s[84:85]
	s_cbranch_execz .LBB0_1276
	s_add_i32 s0, 0, 0x20800
	v_mov_b32_e32 v1, s0
	s_waitcnt vmcnt(0) expcnt(0) lgkmcnt(0)
	ds_read_b32 v3, v1
	s_add_i32 s0, 0, 0x20804
	v_mov_b32_e32 v1, s0
	ds_read_b32 v1, v1
	s_waitcnt lgkmcnt(1)
	v_cmp_ne_u32_e32 vcc, 0, v3
	s_cbranch_vccnz .LBB0_1240
	s_add_u32 s8, s46, 0x80200
	s_addc_u32 s9, s47, 0
	s_add_u32 s10, s46, 0x80400
	s_addc_u32 s11, s47, 0
	s_add_u32 s12, s46, 0x80500
	s_addc_u32 s13, s47, 0
	s_add_u32 s14, s46, 0x80600
	s_addc_u32 s15, s47, 0
	s_add_u32 s16, s46, 0x80700
	s_addc_u32 s17, s47, 0
	s_add_u32 s18, s46, 0x80800
	s_addc_u32 s19, s47, 0
	s_add_u32 s20, s46, 0x80900
	s_addc_u32 s21, s47, 0
	s_add_u32 s22, s46, 0x80a00
	s_addc_u32 s23, s47, 0
	s_add_u32 s24, s46, 0x80b00
	s_addc_u32 s25, s47, 0
	s_add_u32 s26, s46, 0x80c00
	s_addc_u32 s27, s47, 0
	s_add_u32 s28, s46, 0x80d00
	s_addc_u32 s29, s47, 0
	s_add_u32 s30, s46, 0x80e00
	s_addc_u32 s31, s47, 0
	s_add_u32 s34, s46, 0x80f00
	s_addc_u32 s35, s47, 0
	s_add_u32 s36, s46, 0x81000
	s_addc_u32 s37, s47, 0
	s_add_u32 s38, s46, 0x81100
	s_addc_u32 s39, s47, 0
	s_add_u32 s40, s46, 0x81200
	v_readlane_b32 s0, v249, 0
	s_addc_u32 s41, s47, 0
	s_mul_i32 s0, s49, s0
	s_add_u32 s42, s46, 0x81300
	s_mul_i32 s0, s0, s48
	s_addc_u32 s43, s47, 0
	s_mov_b32 s1, 1
	v_mov_b32_e32 v17, 0
	s_branch .LBB0_1228

.LBB0_1289:
.LBB0_1290:
	s_cmp_lt_i32 s50, 7
	s_cselect_b64 s[0:1], -1, 0
	s_and_b64 s[24:25], s[0:1], s[4:5]
	s_andn2_b64 vcc, exec, s[24:25]
	s_cbranch_vccnz .LBB0_1378
	s_cmpk_gt_i32 s2, 0x7ff
	s_cbranch_scc1 .LBB0_1318
	s_and_b32 s52, s2, 15
	v_readfirstlane_b32 s33, v179
	v_mov_b32_e32 v77, 0
	v_and_b32_e32 v184, 63, v178
	v_lshlrev_b32_e32 v230, 1, v184
	v_lshlrev_b32_e32 v231, 2, v184
	v_and_b32_e32 v210, 15, v178
	v_lshrrev_b32_e32 v185, 3, v178
	v_and_b32_e32 v185, 0x3e, v185
	v_lshlrev_b32_e32 v233, 8, v185
	v_lshl_add_u32 v233, v210, 4, v233
	v_lshlrev_b32_e32 v159, 4, v210
	v_lshlrev_b32_e32 v208, 3, v185
	v_add_u32_e32 v208, 0x500, v208
	s_movk_i32 s0, 0x5200
	v_mul_lo_u32 v234, v210, s0
	v_lshl_add_u32 v234, v185, 1, v234
	s_mul_i32 s0, s33, 0x700
	v_add_u32_e32 v235, s0, v231
	v_and_b32_e32 v244, 1, v184
	v_lshlrev_b32_e32 v244, 2, v244
	v_lshrrev_b32_e32 v189, 1, v184
	v_lshl_add_u32 v244, v189, 4, v244
	s_add_i32 s0, s0, 0x500
	v_add_u32_e32 v244, s0, v244
	v_mov_b32_e32 v162, 0
	v_mov_b32_e32 v163, 0
	v_mov_b32_e32 v164, 0
	v_mov_b32_e32 v165, 0
	v_mov_b32_e32 v173, 0
	v_mov_b32_e32 v166, 0
	v_mov_b32_e32 v167, 0
	v_mov_b32_e32 v168, 0
	v_mov_b32_e32 v169, 0
	v_mov_b32_e32 v170, 0
	v_mov_b32_e32 v171, 0
	v_mov_b32_e32 v172, 0
	v_mov_b32_e32 v174, 0
	v_mov_b32_e32 v175, 0
	v_mov_b32_e32 v176, 0
	v_mov_b32_e32 v177, 0
	v_mov_b32_e32 v186, 0x20020
	v_mov_b32_e32 v187, 0x20080
	v_mov_b32_e32 v188, 0x200b0
	ds_read_b128 v[216:219], v186
	ds_read_b64 v[220:221], v187
	ds_read_b128 v[236:239], v188
	s_waitcnt lgkmcnt(0)
	v_readfirstlane_b32 s54, v216
	v_readfirstlane_b32 s55, v217
	v_readfirstlane_b32 s56, v218
	v_readfirstlane_b32 s57, v219
	v_readfirstlane_b32 s58, v220
	v_readfirstlane_b32 s59, v221
	v_readfirstlane_b32 s60, v236
	v_readfirstlane_b32 s61, v237
	v_readfirstlane_b32 s66, v238
	v_readfirstlane_b32 s67, v239
	s_lshl_b32 s0, s52, 8
	s_add_u32 s58, s58, s0
	s_addc_u32 s59, s59, 0
	global_load_dword v224, v231, s[58:59]
	s_add_u32 s58, s58, 0x1000
	s_addc_u32 s59, s59, 0
	global_load_dword v225, v231, s[58:59]
	s_add_u32 s58, s58, 0x1000
	s_addc_u32 s59, s59, 0
	global_load_dword v226, v231, s[58:59]
	s_add_u32 s60, s60, s0
	s_addc_u32 s61, s61, 0
	global_load_dword v227, v231, s[60:61]
	s_add_u32 s66, s66, s0
	s_addc_u32 s67, s67, 0
	global_load_dword v228, v231, s[66:67]
	v_mov_b32_e32 v186, 0x200c0
	ds_read_b64 v[216:217], v186
	s_waitcnt lgkmcnt(0)
	v_readfirstlane_b32 s66, v216
	v_readfirstlane_b32 s67, v217
	s_add_u32 s66, s66, s0
	s_addc_u32 s67, s67, 0
	global_load_dword v247, v231, s[66:67]
	s_mov_b32 s53, s2
	s_mov_b32 s99, 0
	s_lshr_b32 s1, s53, 4
	s_lshl_b32 s0, s1, 3
	s_add_i32 s0, s0, 0x4000
	s_add_i32 s66, s0, s33
	s_lshl_b32 s67, s52, 7
	s_lshl_b32 s60, s53, 14
	s_add_u32 s60, s56, s60
	s_addc_u32 s61, s57, 0
	global_load_dwordx4 v[216:219], v233, s[60:61]
	global_load_dwordx4 v[220:223], v233, s[60:61] offset:256
	s_mul_i32 s58, s66, 0x5200
	s_add_u32 s58, s58, s67
	s_add_u32 s58, s58, 0x5203000
	s_add_u32 s58, s46, s58
	s_addc_u32 s59, s47, 0
	global_load_short_d16_hi v162, v230, s[58:59] offset:-2048
	global_load_short_d16_hi v163, v230, s[58:59]
	global_load_short_d16_hi v164, v230, s[58:59] offset:2048
	s_cmp_eq_u32 s33, 0
	s_cbranch_scc1 .Lrws_shift_a
	s_sub_u32 s60, s58, 0x5200
	s_subb_u32 s61, s59, 0
	global_load_short_d16_hi v175, v230, s[60:61] offset:-2048
	global_load_short_d16_hi v176, v230, s[60:61]
	global_load_short_d16_hi v177, v230, s[60:61] offset:2048
	s_branch .Lrws_shiftdone_a

.Lrws_shiftdone_a:
	s_lshl_b32 s60, s66, 11
	s_add_u32 s60, s60, s67
	s_add_u32 s58, s60, 0x3000000
	s_add_u32 s58, s46, s58
	s_addc_u32 s59, s47, 0
	global_load_short_d16_hi v165, v230, s[58:59]
	s_add_u32 s58, s60, 0x1bb00000
	s_add_u32 s58, s46, s58
	s_addc_u32 s59, s47, 0
	global_load_short_d16_hi v173, v230, s[58:59]
	s_lshl_b32 s60, s0, 11
	s_add_u32 s60, s60, s67
	s_add_u32 s60, s60, 0x3000000
	s_add_u32 s60, s46, s60
	s_addc_u32 s61, s47, 0
	global_load_short_d16_hi v166, v230, s[60:61]
	global_load_short_d16_hi v167, v230, s[60:61] offset:2048
	s_add_u32 s60, s60, 0x1000
	s_addc_u32 s61, s61, 0
	global_load_short_d16_hi v168, v230, s[60:61]
	global_load_short_d16_hi v169, v230, s[60:61] offset:2048
	s_add_u32 s60, s60, 0x1000
	s_addc_u32 s61, s61, 0
	global_load_short_d16_hi v170, v230, s[60:61]
	global_load_short_d16_hi v171, v230, s[60:61] offset:2048
	s_add_u32 s60, s60, 0x1000
	s_addc_u32 s61, s61, 0
	global_load_short_d16_hi v172, v230, s[60:61]
	global_load_short_d16_hi v174, v230, s[60:61] offset:2048
	s_waitcnt vmcnt(0)
	v_sub_f32_e32 v229, 1.0, v228
.Lrws_unit:
	s_waitcnt vmcnt(0)
	v_add_u32_e32 v245, s99, v235
	v_add_u32_e32 v246, s99, v244
	v_add_u32_e32 v156, s99, v159
	v_add_u32_e32 v157, s99, v208
	v_mov_b32_e32 v100, v216
	v_mov_b32_e32 v101, v220
	v_mov_b32_e32 v102, v217
	v_mov_b32_e32 v103, v221
	v_mov_b32_e32 v104, v218
	v_mov_b32_e32 v105, v222
	v_mov_b32_e32 v106, v219
	v_mov_b32_e32 v107, v223
	s_lshr_b32 s1, s53, 4
	s_lshl_b32 s0, s1, 3
	s_add_i32 s0, s0, 0x4000
	s_add_i32 s0, s0, s33
	s_mul_i32 s0, s0, 0x5200
	s_lshl_b32 s1, s52, 7
	s_add_u32 s0, s0, s1
	s_add_u32 s0, s0, 0x5201800
	s_add_u32 s58, s46, s0
	s_addc_u32 s59, s47, 0
	s_cmp_gt_u32 s33, 0
	s_cselect_b32 s0, 1.0, 0
	v_mul_f32_e32 v184, s0, v166
	s_cmp_gt_u32 s33, 1
	s_cselect_b32 s0, 1.0, 0
	v_fmac_f32_e32 v184, s0, v167
	s_cmp_gt_u32 s33, 2
	s_cselect_b32 s0, 1.0, 0
	v_fmac_f32_e32 v184, s0, v168
	s_cmp_gt_u32 s33, 3
	s_cselect_b32 s0, 1.0, 0
	v_fmac_f32_e32 v184, s0, v169
	s_cmp_gt_u32 s33, 4
	s_cselect_b32 s0, 1.0, 0
	v_fmac_f32_e32 v184, s0, v170
	s_cmp_gt_u32 s33, 5
	s_cselect_b32 s0, 1.0, 0
	v_fmac_f32_e32 v184, s0, v171
	s_cmp_gt_u32 s33, 6
	s_cselect_b32 s0, 1.0, 0
	v_fmac_f32_e32 v184, s0, v172
	v_mul_f32_e32 v187, 0xbfb8aa3b, v184
	v_mul_f32_e32 v188, 0x3fb8aa3b, v184
	v_mul_f32_e32 v189, 0xbfb8aa3b, v165
	v_mul_f32_e32 v190, 0x3fb8aa3b, v165
	v_exp_f32_e32 v185, v187
	v_exp_f32_e32 v186, v188
	v_exp_f32_e32 v189, v189
	v_exp_f32_e32 v190, v190
	v_sub_f32_e32 v191, v175, v162
	v_sub_f32_e32 v192, v176, v163
	v_sub_f32_e32 v193, v177, v164
	v_fma_f32 v191, v224, v191, v162
	v_fma_f32 v192, v225, v192, v163
	v_fma_f32 v193, v226, v193, v164
	v_mul_f32_e32 v202, v185, v189
	v_mul_f32_e32 v203, v186, v190
	v_mul_f32_e32 v194, v192, v227
	v_fma_f32 v195, v173, v228, v229
	v_mul_f32_e32 v196, v192, v195
	v_mul_f32_e32 v180, v194, v194
	v_mul_f32_e32 v181, v194, v173
	v_mul_f32_e32 v182, v196, v191
	v_mul_f32_e32 v181, v181, v191
	v_mul_f32_e32 v183, v182, v247
	v_add_f32_dpp v180, v180, v180 quad_perm:[1,0,3,2] row_mask:0xf bank_mask:0xf bound_ctrl:1
	v_add_f32_dpp v181, v181, v181 quad_perm:[1,0,3,2] row_mask:0xf bank_mask:0xf bound_ctrl:1
	v_add_f32_dpp v182, v182, v182 quad_perm:[1,0,3,2] row_mask:0xf bank_mask:0xf bound_ctrl:1
	v_add_f32_dpp v183, v183, v183 quad_perm:[1,0,3,2] row_mask:0xf bank_mask:0xf bound_ctrl:1
	v_add_f32_dpp v180, v180, v180 quad_perm:[2,3,0,1] row_mask:0xf bank_mask:0xf bound_ctrl:1
	v_add_f32_dpp v181, v181, v181 quad_perm:[2,3,0,1] row_mask:0xf bank_mask:0xf bound_ctrl:1
	v_add_f32_dpp v182, v182, v182 quad_perm:[2,3,0,1] row_mask:0xf bank_mask:0xf bound_ctrl:1
	v_add_f32_dpp v183, v183, v183 quad_perm:[2,3,0,1] row_mask:0xf bank_mask:0xf bound_ctrl:1
	v_add_f32_dpp v180, v180, v180 row_half_mirror row_mask:0xf bank_mask:0xf bound_ctrl:1
	v_add_f32_dpp v181, v181, v181 row_half_mirror row_mask:0xf bank_mask:0xf bound_ctrl:1
	v_add_f32_dpp v182, v182, v182 row_half_mirror row_mask:0xf bank_mask:0xf bound_ctrl:1
	v_add_f32_dpp v183, v183, v183 row_half_mirror row_mask:0xf bank_mask:0xf bound_ctrl:1
	v_add_f32_dpp v180, v180, v180 row_mirror row_mask:0xf bank_mask:0xf bound_ctrl:1
	v_add_f32_dpp v181, v181, v181 row_mirror row_mask:0xf bank_mask:0xf bound_ctrl:1
	v_add_f32_dpp v182, v182, v182 row_mirror row_mask:0xf bank_mask:0xf bound_ctrl:1
	v_add_f32_dpp v183, v183, v183 row_mirror row_mask:0xf bank_mask:0xf bound_ctrl:1
	v_add_f32_dpp v180, v180, v180 row_bcast:15 row_mask:0xa bank_mask:0xf
	v_add_f32_dpp v181, v181, v181 row_bcast:15 row_mask:0xa bank_mask:0xf
	v_add_f32_dpp v182, v182, v182 row_bcast:15 row_mask:0xa bank_mask:0xf
	v_add_f32_dpp v183, v183, v183 row_bcast:15 row_mask:0xa bank_mask:0xf
	v_add_f32_dpp v180, v180, v180 row_bcast:31 row_mask:0xc bank_mask:0xf
	v_add_f32_dpp v181, v181, v181 row_bcast:31 row_mask:0xc bank_mask:0xf
	v_add_f32_dpp v182, v182, v182 row_bcast:31 row_mask:0xc bank_mask:0xf
	v_add_f32_dpp v183, v183, v183 row_bcast:31 row_mask:0xc bank_mask:0xf
	v_readlane_b32 s0, v180, 63
	v_readlane_b32 s1, v181, 63
	v_readlane_b32 s66, v182, 63
	v_readlane_b32 s67, v183, 63
	v_mov_b32_e32 v214, s0
	v_mov_b32_e32 v236, s66
	v_sqrt_f32_e32 v214, v214
	v_mul_f32_e32 v237, s67, v193
	v_max_f32_e32 v214, 0x2b8cbccc, v214
	v_rcp_f32_e32 v214, v214
	v_cvt_pk_bf16_f32 v237, v237, v237
	v_mul_f32_e32 v194, v194, v214
	v_mul_f32_e32 v215, s1, v214
	global_store_short v230, v237, s[58:59]
	v_mul_f32_e64 v198, -v194, v185
	v_mul_f32_e32 v197, v194, v173
	v_mul_f32_e32 v199, v202, v191
	v_fmac_f32_e32 v199, v215, v198
	ds_write2st64_b32 v245, v198, v199 offset0:0 offset1:1
	v_mul_f32_e32 v200, v197, v203
	v_mul_f32_e32 v201, v196, v203
	ds_write2st64_b32 v245, v202, v200 offset0:2 offset1:3
	ds_write_b32 v245, v201 offset:1024
	ds_write_b32 v246, v193
	ds_write_b32 v246, v236 offset:8
	s_lshr_b32 s1, s53, 4
	s_lshl_b32 s0, s1, 3
	s_add_i32 s0, s0, 0x4000
	s_mul_i32 s0, s0, 0x5200
	s_lshl_b32 s1, s52, 7
	s_add_u32 s0, s0, s1
	s_add_u32 s0, s0, 0x5201000
	s_add_u32 s100, s46, s0
	s_addc_u32 s101, s47, 0
	s_lshl_b32 s0, s53, 14
	s_add_u32 s0, s0, 0xd4ae000
	s_add_u32 s96, s44, s0
	s_addc_u32 s97, s45, 0
	s_add_i32 s53, s53, s48
	s_cmpk_lt_i32 s53, 0x800
	s_cbranch_scc0 .Lrws_nopf
	s_lshr_b32 s1, s53, 4
	s_lshl_b32 s0, s1, 3
	s_add_i32 s0, s0, 0x4000
	s_add_i32 s66, s0, s33
	s_lshl_b32 s67, s52, 7
	s_lshl_b32 s60, s53, 14
	s_add_u32 s60, s56, s60
	s_addc_u32 s61, s57, 0
	global_load_dwordx4 v[216:219], v233, s[60:61]
	global_load_dwordx4 v[220:223], v233, s[60:61] offset:256
	s_mul_i32 s58, s66, 0x5200
	s_add_u32 s58, s58, s67
	s_add_u32 s58, s58, 0x5203000
	s_add_u32 s58, s46, s58
	s_addc_u32 s59, s47, 0
	global_load_short_d16_hi v162, v230, s[58:59] offset:-2048
	global_load_short_d16_hi v163, v230, s[58:59]
	global_load_short_d16_hi v164, v230, s[58:59] offset:2048
	s_cmp_eq_u32 s33, 0
	s_cbranch_scc1 .Lrws_shift_b
	s_sub_u32 s60, s58, 0x5200
	s_subb_u32 s61, s59, 0
	global_load_short_d16_hi v175, v230, s[60:61] offset:-2048
	global_load_short_d16_hi v176, v230, s[60:61]
	global_load_short_d16_hi v177, v230, s[60:61] offset:2048
	s_branch .Lrws_shiftdone_b

.Lrws_shiftdone_b:
	s_lshl_b32 s60, s66, 11
	s_add_u32 s60, s60, s67
	s_add_u32 s58, s60, 0x3000000
	s_add_u32 s58, s46, s58
	s_addc_u32 s59, s47, 0
	global_load_short_d16_hi v165, v230, s[58:59]
	s_add_u32 s58, s60, 0x1bb00000
	s_add_u32 s58, s46, s58
	s_addc_u32 s59, s47, 0
	global_load_short_d16_hi v173, v230, s[58:59]
	s_lshl_b32 s60, s0, 11
	s_add_u32 s60, s60, s67
	s_add_u32 s60, s60, 0x3000000
	s_add_u32 s60, s46, s60
	s_addc_u32 s61, s47, 0
	global_load_short_d16_hi v166, v230, s[60:61]
	global_load_short_d16_hi v167, v230, s[60:61] offset:2048
	s_add_u32 s60, s60, 0x1000
	s_addc_u32 s61, s61, 0
	global_load_short_d16_hi v168, v230, s[60:61]
	global_load_short_d16_hi v169, v230, s[60:61] offset:2048
	s_add_u32 s60, s60, 0x1000
	s_addc_u32 s61, s61, 0
	global_load_short_d16_hi v170, v230, s[60:61]
	global_load_short_d16_hi v171, v230, s[60:61] offset:2048
	s_add_u32 s60, s60, 0x1000
	s_addc_u32 s61, s61, 0
	global_load_short_d16_hi v172, v230, s[60:61]
	global_load_short_d16_hi v174, v230, s[60:61] offset:2048
.Lrws_nopf:
	s_waitcnt lgkmcnt(0)
	s_barrier
	ds_read_b128 v[108:111], v156 offset:0
	ds_read_b128 v[112:115], v156 offset:256
	ds_read_b128 v[120:123], v156 offset:1024
	ds_read_b128 v[124:127], v157 offset:0
	ds_read_b128 v[116:119], v156 offset:768
	s_waitcnt lgkmcnt(0)
	ds_read_b128 v[128:131], v156 offset:1792
	ds_read_b128 v[132:135], v156 offset:2048
	ds_read_b128 v[140:143], v156 offset:2816
	ds_read_b128 v[144:147], v157 offset:1792
	ds_read_b128 v[136:139], v156 offset:2560
	v_pk_mul_f32 v[148:149], v[100:101], v[108:109] op_sel_hi:[1,0]
	v_pk_mul_f32 v[150:151], v[100:101], v[112:113] op_sel_hi:[1,0]
	v_pk_fma_f32 v[148:149], v[102:103], v[108:109], v[148:149] op_sel:[0,1,0]
	v_pk_fma_f32 v[150:151], v[102:103], v[112:113], v[150:151] op_sel:[0,1,0]
	v_pk_fma_f32 v[148:149], v[104:105], v[110:111], v[148:149] op_sel_hi:[1,0,1]
	v_pk_fma_f32 v[150:151], v[104:105], v[114:115], v[150:151] op_sel_hi:[1,0,1]
	v_pk_fma_f32 v[148:149], v[106:107], v[110:111], v[148:149] op_sel:[0,1,0]
	v_pk_fma_f32 v[150:151], v[106:107], v[114:115], v[150:151] op_sel:[0,1,0]
	v_pk_fma_f32 v[100:101], v[124:125], v[120:121], v[100:101] op_sel_hi:[1,0,1]
	v_add_f32_dpp v148, v148, v148 quad_perm:[1,0,3,2] row_mask:0xf bank_mask:0xf bound_ctrl:1
	v_add_f32_dpp v149, v149, v149 quad_perm:[1,0,3,2] row_mask:0xf bank_mask:0xf bound_ctrl:1
	v_add_f32_dpp v150, v150, v150 quad_perm:[1,0,3,2] row_mask:0xf bank_mask:0xf bound_ctrl:1
	v_add_f32_dpp v151, v151, v151 quad_perm:[1,0,3,2] row_mask:0xf bank_mask:0xf bound_ctrl:1
	v_pk_fma_f32 v[102:103], v[124:125], v[120:121], v[102:103] op_sel:[0,1,0]
	v_add_f32_dpp v148, v148, v148 quad_perm:[2,3,0,1] row_mask:0xf bank_mask:0xf bound_ctrl:1
	v_add_f32_dpp v149, v149, v149 quad_perm:[2,3,0,1] row_mask:0xf bank_mask:0xf bound_ctrl:1
	v_add_f32_dpp v150, v150, v150 quad_perm:[2,3,0,1] row_mask:0xf bank_mask:0xf bound_ctrl:1
	v_add_f32_dpp v151, v151, v151 quad_perm:[2,3,0,1] row_mask:0xf bank_mask:0xf bound_ctrl:1
	v_pk_fma_f32 v[104:105], v[124:125], v[122:123], v[104:105] op_sel_hi:[1,0,1]
	v_add_f32_dpp v148, v148, v148 row_half_mirror row_mask:0xf bank_mask:0xf bound_ctrl:1
	v_add_f32_dpp v149, v149, v149 row_half_mirror row_mask:0xf bank_mask:0xf bound_ctrl:1
	v_add_f32_dpp v150, v150, v150 row_half_mirror row_mask:0xf bank_mask:0xf bound_ctrl:1
	v_add_f32_dpp v151, v151, v151 row_half_mirror row_mask:0xf bank_mask:0xf bound_ctrl:1
	v_pk_fma_f32 v[106:107], v[124:125], v[122:123], v[106:107] op_sel:[0,1,0]
	v_add_f32_dpp v148, v148, v148 row_mirror row_mask:0xf bank_mask:0xf bound_ctrl:1
	v_add_f32_dpp v149, v149, v149 row_mirror row_mask:0xf bank_mask:0xf bound_ctrl:1
	v_add_f32_dpp v150, v150, v150 row_mirror row_mask:0xf bank_mask:0xf bound_ctrl:1
	v_pk_fma_f32 v[100:101], v[148:149], v[116:117], v[100:101] op_sel_hi:[1,0,1]
	v_pk_fma_f32 v[102:103], v[148:149], v[116:117], v[102:103] op_sel:[0,1,0]
	v_pk_fma_f32 v[104:105], v[148:149], v[118:119], v[104:105] op_sel_hi:[1,0,1]
	v_pk_fma_f32 v[106:107], v[148:149], v[118:119], v[106:107] op_sel:[0,1,0]
	v_add_f32_dpp v151, v151, v151 row_mirror row_mask:0xf bank_mask:0xf bound_ctrl:1
	v_pk_fma_f32 v[152:153], v[124:125], v[126:127], v[150:151] op_sel_hi:[1,0,1]
	v_cvt_pk_bf16_f32 v154, v152, v153
	s_waitcnt lgkmcnt(0)
	ds_read_b128 v[108:111], v156 offset:3584
	ds_read_b128 v[112:115], v156 offset:3840
	ds_read_b128 v[120:123], v156 offset:4608
	ds_read_b128 v[124:127], v157 offset:3584
	ds_read_b128 v[116:119], v156 offset:4352
	v_mov_b32_e32 v155, v154
	v_pk_mul_f32 v[148:149], v[100:101], v[128:129] op_sel_hi:[1,0]
	v_pk_mul_f32 v[150:151], v[100:101], v[132:133] op_sel_hi:[1,0]
	v_pk_fma_f32 v[148:149], v[102:103], v[128:129], v[148:149] op_sel:[0,1,0]
	v_pk_fma_f32 v[150:151], v[102:103], v[132:133], v[150:151] op_sel:[0,1,0]
	v_pk_fma_f32 v[148:149], v[104:105], v[130:131], v[148:149] op_sel_hi:[1,0,1]
	v_pk_fma_f32 v[150:151], v[104:105], v[134:135], v[150:151] op_sel_hi:[1,0,1]
	v_pk_fma_f32 v[148:149], v[106:107], v[130:131], v[148:149] op_sel:[0,1,0]
	v_pk_fma_f32 v[150:151], v[106:107], v[134:135], v[150:151] op_sel:[0,1,0]
	v_pk_fma_f32 v[100:101], v[144:145], v[140:141], v[100:101] op_sel_hi:[1,0,1]
	v_add_f32_dpp v148, v148, v148 quad_perm:[1,0,3,2] row_mask:0xf bank_mask:0xf bound_ctrl:1
	v_add_f32_dpp v149, v149, v149 quad_perm:[1,0,3,2] row_mask:0xf bank_mask:0xf bound_ctrl:1
	v_add_f32_dpp v150, v150, v150 quad_perm:[1,0,3,2] row_mask:0xf bank_mask:0xf bound_ctrl:1
	v_add_f32_dpp v151, v151, v151 quad_perm:[1,0,3,2] row_mask:0xf bank_mask:0xf bound_ctrl:1
	v_pk_fma_f32 v[102:103], v[144:145], v[140:141], v[102:103] op_sel:[0,1,0]
	v_add_f32_dpp v148, v148, v148 quad_perm:[2,3,0,1] row_mask:0xf bank_mask:0xf bound_ctrl:1
	v_add_f32_dpp v149, v149, v149 quad_perm:[2,3,0,1] row_mask:0xf bank_mask:0xf bound_ctrl:1
	v_add_f32_dpp v150, v150, v150 quad_perm:[2,3,0,1] row_mask:0xf bank_mask:0xf bound_ctrl:1
	v_add_f32_dpp v151, v151, v151 quad_perm:[2,3,0,1] row_mask:0xf bank_mask:0xf bound_ctrl:1
	v_pk_fma_f32 v[104:105], v[144:145], v[142:143], v[104:105] op_sel_hi:[1,0,1]
	v_add_f32_dpp v148, v148, v148 row_half_mirror row_mask:0xf bank_mask:0xf bound_ctrl:1
	v_add_f32_dpp v149, v149, v149 row_half_mirror row_mask:0xf bank_mask:0xf bound_ctrl:1
	v_add_f32_dpp v150, v150, v150 row_half_mirror row_mask:0xf bank_mask:0xf bound_ctrl:1
	v_add_f32_dpp v151, v151, v151 row_half_mirror row_mask:0xf bank_mask:0xf bound_ctrl:1
	v_pk_fma_f32 v[106:107], v[144:145], v[142:143], v[106:107] op_sel:[0,1,0]
	v_add_f32_dpp v148, v148, v148 row_mirror row_mask:0xf bank_mask:0xf bound_ctrl:1
	v_add_f32_dpp v149, v149, v149 row_mirror row_mask:0xf bank_mask:0xf bound_ctrl:1
	v_add_f32_dpp v150, v150, v150 row_mirror row_mask:0xf bank_mask:0xf bound_ctrl:1
	v_pk_fma_f32 v[100:101], v[148:149], v[136:137], v[100:101] op_sel_hi:[1,0,1]
	v_pk_fma_f32 v[102:103], v[148:149], v[136:137], v[102:103] op_sel:[0,1,0]
	v_pk_fma_f32 v[104:105], v[148:149], v[138:139], v[104:105] op_sel_hi:[1,0,1]
	v_pk_fma_f32 v[106:107], v[148:149], v[138:139], v[106:107] op_sel:[0,1,0]
	v_add_f32_dpp v151, v151, v151 row_mirror row_mask:0xf bank_mask:0xf bound_ctrl:1
	v_pk_fma_f32 v[152:153], v[144:145], v[146:147], v[150:151] op_sel_hi:[1,0,1]
	v_cvt_pk_bf16_f32 v154, v152, v153
	s_waitcnt lgkmcnt(0)
	ds_read_b128 v[128:131], v156 offset:5376
	ds_read_b128 v[132:135], v156 offset:5632
	ds_read_b128 v[140:143], v156 offset:6400
	ds_read_b128 v[144:147], v157 offset:5376
	ds_read_b128 v[136:139], v156 offset:6144
	v_mov_b32_dpp v155, v154 row_shr:1 row_mask:0xf bank_mask:0xf
	v_pk_mul_f32 v[148:149], v[100:101], v[108:109] op_sel_hi:[1,0]
	v_pk_mul_f32 v[150:151], v[100:101], v[112:113] op_sel_hi:[1,0]
	v_pk_fma_f32 v[148:149], v[102:103], v[108:109], v[148:149] op_sel:[0,1,0]
	v_pk_fma_f32 v[150:151], v[102:103], v[112:113], v[150:151] op_sel:[0,1,0]
	v_pk_fma_f32 v[148:149], v[104:105], v[110:111], v[148:149] op_sel_hi:[1,0,1]
	v_pk_fma_f32 v[150:151], v[104:105], v[114:115], v[150:151] op_sel_hi:[1,0,1]
	v_pk_fma_f32 v[148:149], v[106:107], v[110:111], v[148:149] op_sel:[0,1,0]
	v_pk_fma_f32 v[150:151], v[106:107], v[114:115], v[150:151] op_sel:[0,1,0]
	v_pk_fma_f32 v[100:101], v[124:125], v[120:121], v[100:101] op_sel_hi:[1,0,1]
	v_add_f32_dpp v148, v148, v148 quad_perm:[1,0,3,2] row_mask:0xf bank_mask:0xf bound_ctrl:1
	v_add_f32_dpp v149, v149, v149 quad_perm:[1,0,3,2] row_mask:0xf bank_mask:0xf bound_ctrl:1
	v_add_f32_dpp v150, v150, v150 quad_perm:[1,0,3,2] row_mask:0xf bank_mask:0xf bound_ctrl:1
	v_add_f32_dpp v151, v151, v151 quad_perm:[1,0,3,2] row_mask:0xf bank_mask:0xf bound_ctrl:1
	v_pk_fma_f32 v[102:103], v[124:125], v[120:121], v[102:103] op_sel:[0,1,0]
	v_add_f32_dpp v148, v148, v148 quad_perm:[2,3,0,1] row_mask:0xf bank_mask:0xf bound_ctrl:1
	v_add_f32_dpp v149, v149, v149 quad_perm:[2,3,0,1] row_mask:0xf bank_mask:0xf bound_ctrl:1
	v_add_f32_dpp v150, v150, v150 quad_perm:[2,3,0,1] row_mask:0xf bank_mask:0xf bound_ctrl:1
	v_add_f32_dpp v151, v151, v151 quad_perm:[2,3,0,1] row_mask:0xf bank_mask:0xf bound_ctrl:1
	v_pk_fma_f32 v[104:105], v[124:125], v[122:123], v[104:105] op_sel_hi:[1,0,1]
	v_add_f32_dpp v148, v148, v148 row_half_mirror row_mask:0xf bank_mask:0xf bound_ctrl:1
	v_add_f32_dpp v149, v149, v149 row_half_mirror row_mask:0xf bank_mask:0xf bound_ctrl:1
	v_add_f32_dpp v150, v150, v150 row_half_mirror row_mask:0xf bank_mask:0xf bound_ctrl:1
	v_add_f32_dpp v151, v151, v151 row_half_mirror row_mask:0xf bank_mask:0xf bound_ctrl:1
	v_pk_fma_f32 v[106:107], v[124:125], v[122:123], v[106:107] op_sel:[0,1,0]
	v_add_f32_dpp v148, v148, v148 row_mirror row_mask:0xf bank_mask:0xf bound_ctrl:1
	v_add_f32_dpp v149, v149, v149 row_mirror row_mask:0xf bank_mask:0xf bound_ctrl:1
	v_add_f32_dpp v150, v150, v150 row_mirror row_mask:0xf bank_mask:0xf bound_ctrl:1
	v_pk_fma_f32 v[100:101], v[148:149], v[116:117], v[100:101] op_sel_hi:[1,0,1]
	v_pk_fma_f32 v[102:103], v[148:149], v[116:117], v[102:103] op_sel:[0,1,0]
	v_pk_fma_f32 v[104:105], v[148:149], v[118:119], v[104:105] op_sel_hi:[1,0,1]
	v_pk_fma_f32 v[106:107], v[148:149], v[118:119], v[106:107] op_sel:[0,1,0]
	v_add_f32_dpp v151, v151, v151 row_mirror row_mask:0xf bank_mask:0xf bound_ctrl:1
	v_pk_fma_f32 v[152:153], v[124:125], v[126:127], v[150:151] op_sel_hi:[1,0,1]
	v_cvt_pk_bf16_f32 v154, v152, v153
	s_waitcnt lgkmcnt(0)
	ds_read_b128 v[108:111], v156 offset:7168
	ds_read_b128 v[112:115], v156 offset:7424
	ds_read_b128 v[120:123], v156 offset:8192
	ds_read_b128 v[124:127], v157 offset:7168
	ds_read_b128 v[116:119], v156 offset:7936
	v_mov_b32_dpp v155, v154 row_shr:2 row_mask:0xf bank_mask:0xf
	v_pk_mul_f32 v[148:149], v[100:101], v[128:129] op_sel_hi:[1,0]
	v_pk_mul_f32 v[150:151], v[100:101], v[132:133] op_sel_hi:[1,0]
	v_pk_fma_f32 v[148:149], v[102:103], v[128:129], v[148:149] op_sel:[0,1,0]
	v_pk_fma_f32 v[150:151], v[102:103], v[132:133], v[150:151] op_sel:[0,1,0]
	v_pk_fma_f32 v[148:149], v[104:105], v[130:131], v[148:149] op_sel_hi:[1,0,1]
	v_pk_fma_f32 v[150:151], v[104:105], v[134:135], v[150:151] op_sel_hi:[1,0,1]
	v_pk_fma_f32 v[148:149], v[106:107], v[130:131], v[148:149] op_sel:[0,1,0]
	v_pk_fma_f32 v[150:151], v[106:107], v[134:135], v[150:151] op_sel:[0,1,0]
	v_pk_fma_f32 v[100:101], v[144:145], v[140:141], v[100:101] op_sel_hi:[1,0,1]
	v_add_f32_dpp v148, v148, v148 quad_perm:[1,0,3,2] row_mask:0xf bank_mask:0xf bound_ctrl:1
	v_add_f32_dpp v149, v149, v149 quad_perm:[1,0,3,2] row_mask:0xf bank_mask:0xf bound_ctrl:1
	v_add_f32_dpp v150, v150, v150 quad_perm:[1,0,3,2] row_mask:0xf bank_mask:0xf bound_ctrl:1
	v_add_f32_dpp v151, v151, v151 quad_perm:[1,0,3,2] row_mask:0xf bank_mask:0xf bound_ctrl:1
	v_pk_fma_f32 v[102:103], v[144:145], v[140:141], v[102:103] op_sel:[0,1,0]
	v_add_f32_dpp v148, v148, v148 quad_perm:[2,3,0,1] row_mask:0xf bank_mask:0xf bound_ctrl:1
	v_add_f32_dpp v149, v149, v149 quad_perm:[2,3,0,1] row_mask:0xf bank_mask:0xf bound_ctrl:1
	v_add_f32_dpp v150, v150, v150 quad_perm:[2,3,0,1] row_mask:0xf bank_mask:0xf bound_ctrl:1
	v_add_f32_dpp v151, v151, v151 quad_perm:[2,3,0,1] row_mask:0xf bank_mask:0xf bound_ctrl:1
	v_pk_fma_f32 v[104:105], v[144:145], v[142:143], v[104:105] op_sel_hi:[1,0,1]
	v_add_f32_dpp v148, v148, v148 row_half_mirror row_mask:0xf bank_mask:0xf bound_ctrl:1
	v_add_f32_dpp v149, v149, v149 row_half_mirror row_mask:0xf bank_mask:0xf bound_ctrl:1
	v_add_f32_dpp v150, v150, v150 row_half_mirror row_mask:0xf bank_mask:0xf bound_ctrl:1
	v_add_f32_dpp v151, v151, v151 row_half_mirror row_mask:0xf bank_mask:0xf bound_ctrl:1
	v_pk_fma_f32 v[106:107], v[144:145], v[142:143], v[106:107] op_sel:[0,1,0]
	v_add_f32_dpp v148, v148, v148 row_mirror row_mask:0xf bank_mask:0xf bound_ctrl:1
	v_add_f32_dpp v149, v149, v149 row_mirror row_mask:0xf bank_mask:0xf bound_ctrl:1
	v_add_f32_dpp v150, v150, v150 row_mirror row_mask:0xf bank_mask:0xf bound_ctrl:1
	v_pk_fma_f32 v[100:101], v[148:149], v[136:137], v[100:101] op_sel_hi:[1,0,1]
	v_pk_fma_f32 v[102:103], v[148:149], v[136:137], v[102:103] op_sel:[0,1,0]
	v_pk_fma_f32 v[104:105], v[148:149], v[138:139], v[104:105] op_sel_hi:[1,0,1]
	v_pk_fma_f32 v[106:107], v[148:149], v[138:139], v[106:107] op_sel:[0,1,0]
	v_add_f32_dpp v151, v151, v151 row_mirror row_mask:0xf bank_mask:0xf bound_ctrl:1
	v_pk_fma_f32 v[152:153], v[144:145], v[146:147], v[150:151] op_sel_hi:[1,0,1]
	v_cvt_pk_bf16_f32 v154, v152, v153
	s_waitcnt lgkmcnt(0)
	ds_read_b128 v[128:131], v156 offset:8960
	ds_read_b128 v[132:135], v156 offset:9216
	ds_read_b128 v[140:143], v156 offset:9984
	ds_read_b128 v[144:147], v157 offset:8960
	ds_read_b128 v[136:139], v156 offset:9728
	v_mov_b32_dpp v155, v154 row_shr:3 row_mask:0xf bank_mask:0xf
	v_pk_mul_f32 v[148:149], v[100:101], v[108:109] op_sel_hi:[1,0]
	v_pk_mul_f32 v[150:151], v[100:101], v[112:113] op_sel_hi:[1,0]
	v_pk_fma_f32 v[148:149], v[102:103], v[108:109], v[148:149] op_sel:[0,1,0]
	v_pk_fma_f32 v[150:151], v[102:103], v[112:113], v[150:151] op_sel:[0,1,0]
	v_pk_fma_f32 v[148:149], v[104:105], v[110:111], v[148:149] op_sel_hi:[1,0,1]
	v_pk_fma_f32 v[150:151], v[104:105], v[114:115], v[150:151] op_sel_hi:[1,0,1]
	v_pk_fma_f32 v[148:149], v[106:107], v[110:111], v[148:149] op_sel:[0,1,0]
	v_pk_fma_f32 v[150:151], v[106:107], v[114:115], v[150:151] op_sel:[0,1,0]
	v_pk_fma_f32 v[100:101], v[124:125], v[120:121], v[100:101] op_sel_hi:[1,0,1]
	v_add_f32_dpp v148, v148, v148 quad_perm:[1,0,3,2] row_mask:0xf bank_mask:0xf bound_ctrl:1
	v_add_f32_dpp v149, v149, v149 quad_perm:[1,0,3,2] row_mask:0xf bank_mask:0xf bound_ctrl:1
	v_add_f32_dpp v150, v150, v150 quad_perm:[1,0,3,2] row_mask:0xf bank_mask:0xf bound_ctrl:1
	v_add_f32_dpp v151, v151, v151 quad_perm:[1,0,3,2] row_mask:0xf bank_mask:0xf bound_ctrl:1
	v_pk_fma_f32 v[102:103], v[124:125], v[120:121], v[102:103] op_sel:[0,1,0]
	v_add_f32_dpp v148, v148, v148 quad_perm:[2,3,0,1] row_mask:0xf bank_mask:0xf bound_ctrl:1
	v_add_f32_dpp v149, v149, v149 quad_perm:[2,3,0,1] row_mask:0xf bank_mask:0xf bound_ctrl:1
	v_add_f32_dpp v150, v150, v150 quad_perm:[2,3,0,1] row_mask:0xf bank_mask:0xf bound_ctrl:1
	v_add_f32_dpp v151, v151, v151 quad_perm:[2,3,0,1] row_mask:0xf bank_mask:0xf bound_ctrl:1
	v_pk_fma_f32 v[104:105], v[124:125], v[122:123], v[104:105] op_sel_hi:[1,0,1]
	v_add_f32_dpp v148, v148, v148 row_half_mirror row_mask:0xf bank_mask:0xf bound_ctrl:1
	v_add_f32_dpp v149, v149, v149 row_half_mirror row_mask:0xf bank_mask:0xf bound_ctrl:1
	v_add_f32_dpp v150, v150, v150 row_half_mirror row_mask:0xf bank_mask:0xf bound_ctrl:1
	v_add_f32_dpp v151, v151, v151 row_half_mirror row_mask:0xf bank_mask:0xf bound_ctrl:1
	v_pk_fma_f32 v[106:107], v[124:125], v[122:123], v[106:107] op_sel:[0,1,0]
	v_add_f32_dpp v148, v148, v148 row_mirror row_mask:0xf bank_mask:0xf bound_ctrl:1
	v_add_f32_dpp v149, v149, v149 row_mirror row_mask:0xf bank_mask:0xf bound_ctrl:1
	v_add_f32_dpp v150, v150, v150 row_mirror row_mask:0xf bank_mask:0xf bound_ctrl:1
	v_pk_fma_f32 v[100:101], v[148:149], v[116:117], v[100:101] op_sel_hi:[1,0,1]
	v_pk_fma_f32 v[102:103], v[148:149], v[116:117], v[102:103] op_sel:[0,1,0]
	v_pk_fma_f32 v[104:105], v[148:149], v[118:119], v[104:105] op_sel_hi:[1,0,1]
	v_pk_fma_f32 v[106:107], v[148:149], v[118:119], v[106:107] op_sel:[0,1,0]
	v_add_f32_dpp v151, v151, v151 row_mirror row_mask:0xf bank_mask:0xf bound_ctrl:1
	v_pk_fma_f32 v[152:153], v[124:125], v[126:127], v[150:151] op_sel_hi:[1,0,1]
	v_cvt_pk_bf16_f32 v154, v152, v153
	s_waitcnt lgkmcnt(0)
	ds_read_b128 v[108:111], v156 offset:10752
	ds_read_b128 v[112:115], v156 offset:11008
	ds_read_b128 v[120:123], v156 offset:11776
	ds_read_b128 v[124:127], v157 offset:10752
	ds_read_b128 v[116:119], v156 offset:11520
	v_mov_b32_dpp v155, v154 row_shr:4 row_mask:0xf bank_mask:0xf
	v_pk_mul_f32 v[148:149], v[100:101], v[128:129] op_sel_hi:[1,0]
	v_pk_mul_f32 v[150:151], v[100:101], v[132:133] op_sel_hi:[1,0]
	v_pk_fma_f32 v[148:149], v[102:103], v[128:129], v[148:149] op_sel:[0,1,0]
	v_pk_fma_f32 v[150:151], v[102:103], v[132:133], v[150:151] op_sel:[0,1,0]
	v_pk_fma_f32 v[148:149], v[104:105], v[130:131], v[148:149] op_sel_hi:[1,0,1]
	v_pk_fma_f32 v[150:151], v[104:105], v[134:135], v[150:151] op_sel_hi:[1,0,1]
	v_pk_fma_f32 v[148:149], v[106:107], v[130:131], v[148:149] op_sel:[0,1,0]
	v_pk_fma_f32 v[150:151], v[106:107], v[134:135], v[150:151] op_sel:[0,1,0]
	v_pk_fma_f32 v[100:101], v[144:145], v[140:141], v[100:101] op_sel_hi:[1,0,1]
	v_add_f32_dpp v148, v148, v148 quad_perm:[1,0,3,2] row_mask:0xf bank_mask:0xf bound_ctrl:1
	v_add_f32_dpp v149, v149, v149 quad_perm:[1,0,3,2] row_mask:0xf bank_mask:0xf bound_ctrl:1
	v_add_f32_dpp v150, v150, v150 quad_perm:[1,0,3,2] row_mask:0xf bank_mask:0xf bound_ctrl:1
	v_add_f32_dpp v151, v151, v151 quad_perm:[1,0,3,2] row_mask:0xf bank_mask:0xf bound_ctrl:1
	v_pk_fma_f32 v[102:103], v[144:145], v[140:141], v[102:103] op_sel:[0,1,0]
	v_add_f32_dpp v148, v148, v148 quad_perm:[2,3,0,1] row_mask:0xf bank_mask:0xf bound_ctrl:1
	v_add_f32_dpp v149, v149, v149 quad_perm:[2,3,0,1] row_mask:0xf bank_mask:0xf bound_ctrl:1
	v_add_f32_dpp v150, v150, v150 quad_perm:[2,3,0,1] row_mask:0xf bank_mask:0xf bound_ctrl:1
	v_add_f32_dpp v151, v151, v151 quad_perm:[2,3,0,1] row_mask:0xf bank_mask:0xf bound_ctrl:1
	v_pk_fma_f32 v[104:105], v[144:145], v[142:143], v[104:105] op_sel_hi:[1,0,1]
	v_add_f32_dpp v148, v148, v148 row_half_mirror row_mask:0xf bank_mask:0xf bound_ctrl:1
	v_add_f32_dpp v149, v149, v149 row_half_mirror row_mask:0xf bank_mask:0xf bound_ctrl:1
	v_add_f32_dpp v150, v150, v150 row_half_mirror row_mask:0xf bank_mask:0xf bound_ctrl:1
	v_add_f32_dpp v151, v151, v151 row_half_mirror row_mask:0xf bank_mask:0xf bound_ctrl:1
	v_pk_fma_f32 v[106:107], v[144:145], v[142:143], v[106:107] op_sel:[0,1,0]
	v_add_f32_dpp v148, v148, v148 row_mirror row_mask:0xf bank_mask:0xf bound_ctrl:1
	v_add_f32_dpp v149, v149, v149 row_mirror row_mask:0xf bank_mask:0xf bound_ctrl:1
	v_add_f32_dpp v150, v150, v150 row_mirror row_mask:0xf bank_mask:0xf bound_ctrl:1
	v_pk_fma_f32 v[100:101], v[148:149], v[136:137], v[100:101] op_sel_hi:[1,0,1]
	v_pk_fma_f32 v[102:103], v[148:149], v[136:137], v[102:103] op_sel:[0,1,0]
	v_pk_fma_f32 v[104:105], v[148:149], v[138:139], v[104:105] op_sel_hi:[1,0,1]
	v_pk_fma_f32 v[106:107], v[148:149], v[138:139], v[106:107] op_sel:[0,1,0]
	v_add_f32_dpp v151, v151, v151 row_mirror row_mask:0xf bank_mask:0xf bound_ctrl:1
	v_pk_fma_f32 v[152:153], v[144:145], v[146:147], v[150:151] op_sel_hi:[1,0,1]
	v_cvt_pk_bf16_f32 v154, v152, v153
	s_waitcnt lgkmcnt(0)
	ds_read_b128 v[128:131], v156 offset:12544
	ds_read_b128 v[132:135], v156 offset:12800
	ds_read_b128 v[140:143], v156 offset:13568
	ds_read_b128 v[144:147], v157 offset:12544
	ds_read_b128 v[136:139], v156 offset:13312
	v_mov_b32_dpp v155, v154 row_shr:5 row_mask:0xf bank_mask:0xf
	v_pk_mul_f32 v[148:149], v[100:101], v[108:109] op_sel_hi:[1,0]
	v_pk_mul_f32 v[150:151], v[100:101], v[112:113] op_sel_hi:[1,0]
	v_pk_fma_f32 v[148:149], v[102:103], v[108:109], v[148:149] op_sel:[0,1,0]
	v_pk_fma_f32 v[150:151], v[102:103], v[112:113], v[150:151] op_sel:[0,1,0]
	v_pk_fma_f32 v[148:149], v[104:105], v[110:111], v[148:149] op_sel_hi:[1,0,1]
	v_pk_fma_f32 v[150:151], v[104:105], v[114:115], v[150:151] op_sel_hi:[1,0,1]
	v_pk_fma_f32 v[148:149], v[106:107], v[110:111], v[148:149] op_sel:[0,1,0]
	v_pk_fma_f32 v[150:151], v[106:107], v[114:115], v[150:151] op_sel:[0,1,0]
	v_pk_fma_f32 v[100:101], v[124:125], v[120:121], v[100:101] op_sel_hi:[1,0,1]
	v_add_f32_dpp v148, v148, v148 quad_perm:[1,0,3,2] row_mask:0xf bank_mask:0xf bound_ctrl:1
	v_add_f32_dpp v149, v149, v149 quad_perm:[1,0,3,2] row_mask:0xf bank_mask:0xf bound_ctrl:1
	v_add_f32_dpp v150, v150, v150 quad_perm:[1,0,3,2] row_mask:0xf bank_mask:0xf bound_ctrl:1
	v_add_f32_dpp v151, v151, v151 quad_perm:[1,0,3,2] row_mask:0xf bank_mask:0xf bound_ctrl:1
	v_pk_fma_f32 v[102:103], v[124:125], v[120:121], v[102:103] op_sel:[0,1,0]
	v_add_f32_dpp v148, v148, v148 quad_perm:[2,3,0,1] row_mask:0xf bank_mask:0xf bound_ctrl:1
	v_add_f32_dpp v149, v149, v149 quad_perm:[2,3,0,1] row_mask:0xf bank_mask:0xf bound_ctrl:1
	v_add_f32_dpp v150, v150, v150 quad_perm:[2,3,0,1] row_mask:0xf bank_mask:0xf bound_ctrl:1
	v_add_f32_dpp v151, v151, v151 quad_perm:[2,3,0,1] row_mask:0xf bank_mask:0xf bound_ctrl:1
	v_pk_fma_f32 v[104:105], v[124:125], v[122:123], v[104:105] op_sel_hi:[1,0,1]
	v_add_f32_dpp v148, v148, v148 row_half_mirror row_mask:0xf bank_mask:0xf bound_ctrl:1
	v_add_f32_dpp v149, v149, v149 row_half_mirror row_mask:0xf bank_mask:0xf bound_ctrl:1
	v_add_f32_dpp v150, v150, v150 row_half_mirror row_mask:0xf bank_mask:0xf bound_ctrl:1
	v_add_f32_dpp v151, v151, v151 row_half_mirror row_mask:0xf bank_mask:0xf bound_ctrl:1
	v_pk_fma_f32 v[106:107], v[124:125], v[122:123], v[106:107] op_sel:[0,1,0]
	v_add_f32_dpp v148, v148, v148 row_mirror row_mask:0xf bank_mask:0xf bound_ctrl:1
	v_add_f32_dpp v149, v149, v149 row_mirror row_mask:0xf bank_mask:0xf bound_ctrl:1
	v_add_f32_dpp v150, v150, v150 row_mirror row_mask:0xf bank_mask:0xf bound_ctrl:1
	v_pk_fma_f32 v[100:101], v[148:149], v[116:117], v[100:101] op_sel_hi:[1,0,1]
	v_pk_fma_f32 v[102:103], v[148:149], v[116:117], v[102:103] op_sel:[0,1,0]
	v_pk_fma_f32 v[104:105], v[148:149], v[118:119], v[104:105] op_sel_hi:[1,0,1]
	v_pk_fma_f32 v[106:107], v[148:149], v[118:119], v[106:107] op_sel:[0,1,0]
	v_add_f32_dpp v151, v151, v151 row_mirror row_mask:0xf bank_mask:0xf bound_ctrl:1
	v_pk_fma_f32 v[152:153], v[124:125], v[126:127], v[150:151] op_sel_hi:[1,0,1]
	v_cvt_pk_bf16_f32 v154, v152, v153
	s_waitcnt lgkmcnt(0)
	ds_read_b128 v[204:207], v156 offset:13056
	s_nop 0
	v_mov_b32_dpp v155, v154 row_shr:6 row_mask:0xf bank_mask:0xf
	v_pk_mul_f32 v[148:149], v[100:101], v[128:129] op_sel_hi:[1,0]
	v_pk_mul_f32 v[150:151], v[100:101], v[132:133] op_sel_hi:[1,0]
	v_pk_fma_f32 v[148:149], v[102:103], v[128:129], v[148:149] op_sel:[0,1,0]
	v_pk_fma_f32 v[150:151], v[102:103], v[132:133], v[150:151] op_sel:[0,1,0]
	v_pk_fma_f32 v[148:149], v[104:105], v[130:131], v[148:149] op_sel_hi:[1,0,1]
	v_pk_fma_f32 v[150:151], v[104:105], v[134:135], v[150:151] op_sel_hi:[1,0,1]
	v_pk_fma_f32 v[148:149], v[106:107], v[130:131], v[148:149] op_sel:[0,1,0]
	v_pk_fma_f32 v[150:151], v[106:107], v[134:135], v[150:151] op_sel:[0,1,0]
	v_pk_fma_f32 v[100:101], v[144:145], v[140:141], v[100:101] op_sel_hi:[1,0,1]
	v_add_f32_dpp v148, v148, v148 quad_perm:[1,0,3,2] row_mask:0xf bank_mask:0xf bound_ctrl:1
	v_add_f32_dpp v149, v149, v149 quad_perm:[1,0,3,2] row_mask:0xf bank_mask:0xf bound_ctrl:1
	v_add_f32_dpp v150, v150, v150 quad_perm:[1,0,3,2] row_mask:0xf bank_mask:0xf bound_ctrl:1
	v_add_f32_dpp v151, v151, v151 quad_perm:[1,0,3,2] row_mask:0xf bank_mask:0xf bound_ctrl:1
	v_pk_fma_f32 v[102:103], v[144:145], v[140:141], v[102:103] op_sel:[0,1,0]
	v_add_f32_dpp v148, v148, v148 quad_perm:[2,3,0,1] row_mask:0xf bank_mask:0xf bound_ctrl:1
	v_add_f32_dpp v149, v149, v149 quad_perm:[2,3,0,1] row_mask:0xf bank_mask:0xf bound_ctrl:1
	v_add_f32_dpp v150, v150, v150 quad_perm:[2,3,0,1] row_mask:0xf bank_mask:0xf bound_ctrl:1
	v_add_f32_dpp v151, v151, v151 quad_perm:[2,3,0,1] row_mask:0xf bank_mask:0xf bound_ctrl:1
	v_pk_fma_f32 v[104:105], v[144:145], v[142:143], v[104:105] op_sel_hi:[1,0,1]
	v_add_f32_dpp v148, v148, v148 row_half_mirror row_mask:0xf bank_mask:0xf bound_ctrl:1
	v_add_f32_dpp v149, v149, v149 row_half_mirror row_mask:0xf bank_mask:0xf bound_ctrl:1
	v_add_f32_dpp v150, v150, v150 row_half_mirror row_mask:0xf bank_mask:0xf bound_ctrl:1
	v_add_f32_dpp v151, v151, v151 row_half_mirror row_mask:0xf bank_mask:0xf bound_ctrl:1
	v_pk_fma_f32 v[106:107], v[144:145], v[142:143], v[106:107] op_sel:[0,1,0]
	v_add_f32_dpp v148, v148, v148 row_mirror row_mask:0xf bank_mask:0xf bound_ctrl:1
	v_add_f32_dpp v149, v149, v149 row_mirror row_mask:0xf bank_mask:0xf bound_ctrl:1
	v_add_f32_dpp v150, v150, v150 row_mirror row_mask:0xf bank_mask:0xf bound_ctrl:1
	v_pk_fma_f32 v[100:101], v[148:149], v[136:137], v[100:101] op_sel_hi:[1,0,1]
	v_pk_fma_f32 v[102:103], v[148:149], v[136:137], v[102:103] op_sel:[0,1,0]
	v_pk_fma_f32 v[104:105], v[148:149], v[138:139], v[104:105] op_sel_hi:[1,0,1]
	v_pk_fma_f32 v[106:107], v[148:149], v[138:139], v[106:107] op_sel:[0,1,0]
	v_add_f32_dpp v151, v151, v151 row_mirror row_mask:0xf bank_mask:0xf bound_ctrl:1
	v_pk_fma_f32 v[152:153], v[144:145], v[146:147], v[150:151] op_sel_hi:[1,0,1]
	v_cvt_pk_bf16_f32 v154, v152, v153
	s_waitcnt lgkmcnt(0)
	v_pk_mul_f32 v[100:101], v[100:101], v[204:205] op_sel_hi:[1,0]
	v_pk_mul_f32 v[102:103], v[102:103], v[204:205] op_sel:[0,1]
	v_pk_mul_f32 v[104:105], v[104:105], v[206:207] op_sel_hi:[1,0]
	v_pk_mul_f32 v[106:107], v[106:107], v[206:207] op_sel:[0,1]
	v_mov_b32_dpp v155, v154 row_shr:7 row_mask:0xf bank_mask:0xf
	s_mov_b32 s0, 0xff00ff
	s_mov_b32 s1, 0xff00ff
	s_mov_b64 exec, s[0:1]
	global_store_dword v234, v155, s[100:101]
	s_mov_b64 exec, -1
	v_mov_b32_e32 v236, v100
	v_mov_b32_e32 v240, v101
	v_mov_b32_e32 v237, v102
	v_mov_b32_e32 v241, v103
	v_mov_b32_e32 v238, v104
	v_mov_b32_e32 v242, v105
	v_mov_b32_e32 v239, v106
	v_mov_b32_e32 v243, v107
	global_store_dwordx4 v233, v[236:239], s[96:97]
	global_store_dwordx4 v233, v[240:243], s[96:97] offset:256
	s_xor_b32 s99, s99, 0x3800
	s_cmpk_lt_i32 s53, 0x800
	s_cbranch_scc1 .Lrws_unit
	s_waitcnt lgkmcnt(0)
	s_barrier

.LBB0_1321:
	ds_read_b64 v[6:7], v75
	ds_read_b128 v[2:5], v195
	s_ashr_i32 s40, s72, 1
	s_and_b32 s73, s40, 15
	v_lshl_or_b32 v42, s73, 6, v1
	s_waitcnt lgkmcnt(0)
	v_readfirstlane_b32 s0, v6
	v_readfirstlane_b32 s1, v7
	v_lshlrev_b32_e32 v76, 2, v42
	s_lshl_b32 s41, s72, 6
	v_lshl_add_u64 v[6:7], s[0:1], 0, v[76:77]
	v_add_co_u32_e32 v8, vcc, s67, v6
	s_waitcnt lgkmcnt(0)
	v_readfirstlane_b32 s0, v2
	v_addc_co_u32_e32 v9, vcc, 0, v7, vcc
	v_readfirstlane_b32 s1, v3
	v_add_co_u32_e32 v10, vcc, s68, v6
	s_nop 0
	v_lshl_add_u64 v[2:3], s[0:1], 0, v[76:77]
	v_readfirstlane_b32 s0, v4
	v_readfirstlane_b32 s1, v5
	v_addc_co_u32_e32 v11, vcc, 0, v7, vcc
	s_waitcnt vmcnt(0)
	flat_load_dword v196, v[6:7]
	flat_load_dword v197, v[8:9]
	flat_load_dword v198, v[10:11]
	flat_load_dword v199, v[2:3]
	v_lshl_add_u64 v[2:3], s[0:1], 0, v[76:77]
	flat_load_dword v200, v[2:3]
	s_and_b32 s42, s41, 0xfffff800
	s_and_saveexec_b64 s[0:1], s[4:5]
	s_xor_b64 s[56:57], exec, s[0:1]
	s_setprio 2
	s_lshl_b32 s30, s73, 2
	v_add_u32_e32 v80, s42, v165
	s_or_saveexec_b64 s[56:57], s[56:57]
	v_mov_b64_e32 v[10:11], s[30:31]
	s_xor_b64 exec, exec, s[56:57]
	s_cbranch_execz .LBB0_1345
	v_mov_b32_e32 v100, 0
	v_mov_b32_e32 v101, 0
	v_mov_b32_e32 v102, 0
	v_mov_b32_e32 v103, 0
	v_mov_b32_e32 v104, 0
	v_mov_b32_e32 v105, 0
	v_mov_b32_e32 v106, 0
	v_mov_b32_e32 v107, 0
	v_mov_b32_e32 v108, 0
	v_mov_b32_e32 v109, 0
	v_mov_b32_e32 v110, 0
	v_mov_b32_e32 v111, 0
	v_mov_b32_e32 v112, 0
	v_mov_b32_e32 v113, 0
	v_mov_b32_e32 v114, 0
	v_mov_b32_e32 v115, 0
	v_mov_b32_e32 v116, 0
	v_mov_b32_e32 v117, 0
	v_mov_b32_e32 v118, 0
	v_mov_b32_e32 v119, 0
	v_mov_b32_e32 v120, 0
	v_mov_b32_e32 v121, 0
	v_mov_b32_e32 v122, 0
	v_mov_b32_e32 v123, 0
	v_mov_b32_e32 v124, 0
	v_mov_b32_e32 v125, 0
	v_mov_b32_e32 v126, 0
	v_mov_b32_e32 v127, 0
	v_mov_b32_e32 v128, 0
	v_mov_b32_e32 v129, 0
	v_mov_b32_e32 v130, 0
	v_mov_b32_e32 v131, 0
	v_mov_b32_e32 v132, 0
	v_mov_b32_e32 v133, 0
	v_mov_b32_e32 v134, 0
	v_mov_b32_e32 v135, 0
	v_mov_b32_e32 v136, 0
	v_mov_b32_e32 v137, 0
	v_mov_b32_e32 v138, 0
	v_mov_b32_e32 v139, 0
	v_mov_b32_e32 v172, 0
	v_mov_b32_e32 v173, 0
	v_mov_b32_e32 v174, 0
	v_lshlrev_b32_e32 v175, 1, v1
	v_add_u32_e32 v224, -4, v179
	v_mul_u32_u24_e32 v224, 0x3800, v224
	v_and_b32_e32 v225, 1, v1
	v_lshlrev_b32_e32 v225, 2, v225
	v_lshrrev_b32_e32 v204, 1, v1
	v_lshl_add_u32 v225, v204, 4, v225
	v_add_u32_e32 v225, v225, v224
	v_add_u32_e32 v225, 0x500, v225
	v_lshl_add_u32 v224, v1, 2, v224
	v_readfirstlane_b32 s33, v179
	s_nop 0
	s_sub_u32 s33, s33, 4
	s_lshl_b32 s41, s33, 3
	s_add_u32 s41, s41, s42
	s_lshl_b32 s0, s73, 7
	s_mul_i32 s1, s41, 0x5200
	s_add_u32 s1, s1, s0
	s_add_u32 s1, s1, 0x3000
	s_add_u32 s98, s20, s1
	s_addc_u32 s99, s21, 0
	s_lshl_b32 s1, s41, 11
	s_add_u32 s1, s1, s0
	s_add_u32 s100, s22, s1
	s_addc_u32 s101, s23, 0
	s_add_u32 s58, s26, s1
	s_addc_u32 s59, s27, 0
	s_mul_i32 s1, s41, 0x5200
	s_lshl_b32 s0, s73, 7
	s_add_u32 s1, s1, s0
	s_add_u32 s1, s1, 0x1800
	s_add_u32 s14, s20, s1
	s_addc_u32 s15, s21, 0
	v_mov_b32_e32 v204, 0x200c0
	ds_read_b64 v[228:229], v204
	v_lshlrev_b32_e32 v205, 2, v1
	s_waitcnt lgkmcnt(0)
	v_readfirstlane_b32 s0, v228
	v_readfirstlane_b32 s1, v229
	s_lshl_b32 s6, s73, 8
	s_add_u32 s0, s0, s6
	s_addc_u32 s1, s1, 0
	global_load_dword v226, v205, s[0:1]
	s_sub_u32 s0, s98, 0x5200
	s_subb_u32 s1, s99, 0
	s_cmp_eq_u32 s33, 0
	s_cbranch_scc1 .Lrwq_noq0_a
	global_load_short_d16_hi v172, v175, s[0:1] offset:-2048
	global_load_short_d16_hi v173, v175, s[0:1]
	global_load_short_d16_hi v174, v175, s[0:1] offset:2048
.Lrwq_noq0_a:
	s_add_u32 s0, s0, 0x5200
	s_addc_u32 s1, s1, 0
	global_load_short_d16_hi v100, v175, s[0:1] offset:-2048
	global_load_short_d16_hi v108, v175, s[0:1]
	global_load_short_d16_hi v116, v175, s[0:1] offset:2048
	s_add_u32 s0, s0, 0x5200
	s_addc_u32 s1, s1, 0
	global_load_short_d16_hi v101, v175, s[0:1] offset:-2048
	global_load_short_d16_hi v109, v175, s[0:1]
	global_load_short_d16_hi v117, v175, s[0:1] offset:2048
	s_add_u32 s0, s0, 0x5200
	s_addc_u32 s1, s1, 0
	global_load_short_d16_hi v102, v175, s[0:1] offset:-2048
	global_load_short_d16_hi v110, v175, s[0:1]
	global_load_short_d16_hi v118, v175, s[0:1] offset:2048
	s_add_u32 s0, s0, 0x5200
	s_addc_u32 s1, s1, 0
	global_load_short_d16_hi v103, v175, s[0:1] offset:-2048
	global_load_short_d16_hi v111, v175, s[0:1]
	global_load_short_d16_hi v119, v175, s[0:1] offset:2048
	s_add_u32 s0, s0, 0x5200
	s_addc_u32 s1, s1, 0
	global_load_short_d16_hi v104, v175, s[0:1] offset:-2048
	global_load_short_d16_hi v112, v175, s[0:1]
	global_load_short_d16_hi v120, v175, s[0:1] offset:2048
	s_add_u32 s0, s0, 0x5200
	s_addc_u32 s1, s1, 0
	global_load_short_d16_hi v105, v175, s[0:1] offset:-2048
	global_load_short_d16_hi v113, v175, s[0:1]
	global_load_short_d16_hi v121, v175, s[0:1] offset:2048
	s_add_u32 s0, s0, 0x5200
	s_addc_u32 s1, s1, 0
	global_load_short_d16_hi v106, v175, s[0:1] offset:-2048
	global_load_short_d16_hi v114, v175, s[0:1]
	global_load_short_d16_hi v122, v175, s[0:1] offset:2048
	s_add_u32 s0, s0, 0x5200
	s_addc_u32 s1, s1, 0
	global_load_short_d16_hi v107, v175, s[0:1] offset:-2048
	global_load_short_d16_hi v115, v175, s[0:1]
	global_load_short_d16_hi v123, v175, s[0:1] offset:2048
	s_add_u32 s0, s100, 0x0
	s_addc_u32 s1, s101, 0
	global_load_short_d16_hi v124, v175, s[0:1]
	global_load_short_d16_hi v125, v175, s[0:1] offset:2048
	s_add_u32 s0, s58, 0x0
	s_addc_u32 s1, s59, 0
	global_load_short_d16_hi v132, v175, s[0:1]
	global_load_short_d16_hi v133, v175, s[0:1] offset:2048
	s_add_u32 s0, s100, 0x1000
	s_addc_u32 s1, s101, 0
	global_load_short_d16_hi v126, v175, s[0:1]
	global_load_short_d16_hi v127, v175, s[0:1] offset:2048
	s_add_u32 s0, s58, 0x1000
	s_addc_u32 s1, s59, 0
	global_load_short_d16_hi v134, v175, s[0:1]
	global_load_short_d16_hi v135, v175, s[0:1] offset:2048
	s_add_u32 s0, s100, 0x2000
	s_addc_u32 s1, s101, 0
	global_load_short_d16_hi v128, v175, s[0:1]
	global_load_short_d16_hi v129, v175, s[0:1] offset:2048
	s_add_u32 s0, s58, 0x2000
	s_addc_u32 s1, s59, 0
	global_load_short_d16_hi v136, v175, s[0:1]
	global_load_short_d16_hi v137, v175, s[0:1] offset:2048
	s_add_u32 s0, s100, 0x3000
	s_addc_u32 s1, s101, 0
	global_load_short_d16_hi v130, v175, s[0:1]
	global_load_short_d16_hi v131, v175, s[0:1] offset:2048
	s_add_u32 s0, s58, 0x3000
	s_addc_u32 s1, s59, 0
	global_load_short_d16_hi v138, v175, s[0:1]
	global_load_short_d16_hi v139, v175, s[0:1] offset:2048
	s_add_u32 s98, s98, 0xa4000
	s_addc_u32 s99, s99, 0
	s_add_u32 s100, s100, 0x10000
	s_addc_u32 s101, s101, 0
	s_add_u32 s58, s58, 0x10000
	s_addc_u32 s59, s59, 0
	s_waitcnt vmcnt(0)
	v_sub_f32_e32 v221, 1.0, v200
	s_mov_b32 s0, 0
	s_waitcnt vmcnt(0)
	v_add_u32_e32 v222, s0, v224
	v_add_u32_e32 v223, s0, v225
	s_mov_b64 s[6:7], s[14:15]
	v_mul_f32_e32 v204, 0xbfb8aa3b, v124
	v_mul_f32_e32 v205, 0x3fb8aa3b, v124
	v_sub_f32_e32 v208, v172, v100
	v_exp_f32_e32 v211, v204
	v_exp_f32_e32 v212, v205
	v_sub_f32_e32 v209, v173, v108
	v_sub_f32_e32 v210, v174, v116
	v_fma_f32 v208, v196, v208, v100
	v_fma_f32 v209, v197, v209, v108
	v_fma_f32 v210, v198, v210, v116
	v_mul_f32_e32 v213, v209, v199
	v_fma_f32 v214, v132, v200, v221
	v_mul_f32_e32 v215, v209, v214
	v_mul_f32_e32 v227, v213, v213
	v_mul_f32_e32 v228, v213, v132
	v_mul_f32_e32 v229, v215, v208
	v_mul_f32_e32 v228, v228, v208
	v_mul_f32_e32 v230, v229, v226
	v_add_f32_dpp v227, v227, v227 quad_perm:[1,0,3,2] row_mask:0xf bank_mask:0xf bound_ctrl:1
	v_add_f32_dpp v228, v228, v228 quad_perm:[1,0,3,2] row_mask:0xf bank_mask:0xf bound_ctrl:1
	v_add_f32_dpp v229, v229, v229 quad_perm:[1,0,3,2] row_mask:0xf bank_mask:0xf bound_ctrl:1
	v_add_f32_dpp v230, v230, v230 quad_perm:[1,0,3,2] row_mask:0xf bank_mask:0xf bound_ctrl:1
	v_add_f32_dpp v227, v227, v227 quad_perm:[2,3,0,1] row_mask:0xf bank_mask:0xf bound_ctrl:1
	v_add_f32_dpp v228, v228, v228 quad_perm:[2,3,0,1] row_mask:0xf bank_mask:0xf bound_ctrl:1
	v_add_f32_dpp v229, v229, v229 quad_perm:[2,3,0,1] row_mask:0xf bank_mask:0xf bound_ctrl:1
	v_add_f32_dpp v230, v230, v230 quad_perm:[2,3,0,1] row_mask:0xf bank_mask:0xf bound_ctrl:1
	v_add_f32_dpp v227, v227, v227 row_half_mirror row_mask:0xf bank_mask:0xf bound_ctrl:1
	v_add_f32_dpp v228, v228, v228 row_half_mirror row_mask:0xf bank_mask:0xf bound_ctrl:1
	v_add_f32_dpp v229, v229, v229 row_half_mirror row_mask:0xf bank_mask:0xf bound_ctrl:1
	v_add_f32_dpp v230, v230, v230 row_half_mirror row_mask:0xf bank_mask:0xf bound_ctrl:1
	v_add_f32_dpp v227, v227, v227 row_mirror row_mask:0xf bank_mask:0xf bound_ctrl:1
	v_add_f32_dpp v228, v228, v228 row_mirror row_mask:0xf bank_mask:0xf bound_ctrl:1
	v_add_f32_dpp v229, v229, v229 row_mirror row_mask:0xf bank_mask:0xf bound_ctrl:1
	v_add_f32_dpp v230, v230, v230 row_mirror row_mask:0xf bank_mask:0xf bound_ctrl:1
	v_add_f32_dpp v227, v227, v227 row_bcast:15 row_mask:0xa bank_mask:0xf
	v_add_f32_dpp v228, v228, v228 row_bcast:15 row_mask:0xa bank_mask:0xf
	v_add_f32_dpp v229, v229, v229 row_bcast:15 row_mask:0xa bank_mask:0xf
	v_add_f32_dpp v230, v230, v230 row_bcast:15 row_mask:0xa bank_mask:0xf
	v_add_f32_dpp v227, v227, v227 row_bcast:31 row_mask:0xc bank_mask:0xf
	v_add_f32_dpp v228, v228, v228 row_bcast:31 row_mask:0xc bank_mask:0xf
	v_add_f32_dpp v229, v229, v229 row_bcast:31 row_mask:0xc bank_mask:0xf
	v_add_f32_dpp v230, v230, v230 row_bcast:31 row_mask:0xc bank_mask:0xf
	v_readlane_b32 s0, v227, 63
	v_readlane_b32 s1, v228, 63
	v_readlane_b32 s33, v229, 63
	v_readlane_b32 s41, v230, 63
	v_mov_b32_e32 v231, s0
	v_mov_b32_e32 v234, s33
	v_sqrt_f32_e32 v231, v231
	v_mul_f32_e32 v235, s41, v210
	v_max_f32_e32 v231, 0x2b8cbccc, v231
	v_rcp_f32_e32 v231, v231
	v_cvt_pk_bf16_f32 v235, v235, v235
	v_mul_f32_e32 v213, v213, v231
	v_mul_f32_e32 v233, s1, v231
	v_mul_f32_e32 v217, -1.0, v213
	v_mul_f32_e32 v216, v213, v132
	v_mul_f32_e32 v218, v211, v208
	v_fmac_f32_e32 v218, v233, v217
	ds_write2st64_b32 v222, v217, v218 offset0:0 offset1:1
	v_mul_f32_e32 v219, v216, v212
	v_mul_f32_e32 v220, v215, v212
	ds_write2st64_b32 v222, v211, v219 offset0:2 offset1:3
	ds_write_b32 v222, v220 offset:1024
	ds_write_b32 v223, v210 offset:0
	ds_write_b32 v223, v234 offset:8
	s_bitcmp1_b32 s72, 0
	s_cbranch_scc1 .Lrwq_nobv_0_p
	global_store_short v175, v235, s[6:7]
.Lrwq_nobv_0_p:
	s_add_u32 s6, s6, 0x5200
	s_addc_u32 s7, s7, 0
	v_mul_f32_e32 v204, 0xbfb8aa3b, v125
	v_mul_f32_e32 v205, 0x3fb8aa3b, v125
	v_sub_f32_e32 v208, v100, v101
	v_exp_f32_e32 v206, v204
	v_exp_f32_e32 v207, v205
	v_sub_f32_e32 v209, v108, v109
	v_sub_f32_e32 v210, v116, v117
	v_fma_f32 v208, v196, v208, v101
	v_fma_f32 v209, v197, v209, v109
	v_fma_f32 v210, v198, v210, v117
	v_mul_f32_e32 v213, v209, v199
	v_fma_f32 v214, v133, v200, v221
	v_mul_f32_e32 v215, v209, v214
	v_mul_f32_e32 v227, v213, v213
	v_mul_f32_e32 v228, v213, v133
	v_mul_f32_e32 v229, v215, v208
	v_mul_f32_e32 v228, v228, v208
	v_mul_f32_e32 v230, v229, v226
	v_add_f32_dpp v227, v227, v227 quad_perm:[1,0,3,2] row_mask:0xf bank_mask:0xf bound_ctrl:1
	v_add_f32_dpp v228, v228, v228 quad_perm:[1,0,3,2] row_mask:0xf bank_mask:0xf bound_ctrl:1
	v_add_f32_dpp v229, v229, v229 quad_perm:[1,0,3,2] row_mask:0xf bank_mask:0xf bound_ctrl:1
	v_add_f32_dpp v230, v230, v230 quad_perm:[1,0,3,2] row_mask:0xf bank_mask:0xf bound_ctrl:1
	v_add_f32_dpp v227, v227, v227 quad_perm:[2,3,0,1] row_mask:0xf bank_mask:0xf bound_ctrl:1
	v_add_f32_dpp v228, v228, v228 quad_perm:[2,3,0,1] row_mask:0xf bank_mask:0xf bound_ctrl:1
	v_add_f32_dpp v229, v229, v229 quad_perm:[2,3,0,1] row_mask:0xf bank_mask:0xf bound_ctrl:1
	v_add_f32_dpp v230, v230, v230 quad_perm:[2,3,0,1] row_mask:0xf bank_mask:0xf bound_ctrl:1
	v_add_f32_dpp v227, v227, v227 row_half_mirror row_mask:0xf bank_mask:0xf bound_ctrl:1
	v_add_f32_dpp v228, v228, v228 row_half_mirror row_mask:0xf bank_mask:0xf bound_ctrl:1
	v_add_f32_dpp v229, v229, v229 row_half_mirror row_mask:0xf bank_mask:0xf bound_ctrl:1
	v_add_f32_dpp v230, v230, v230 row_half_mirror row_mask:0xf bank_mask:0xf bound_ctrl:1
	v_add_f32_dpp v227, v227, v227 row_mirror row_mask:0xf bank_mask:0xf bound_ctrl:1
	v_add_f32_dpp v228, v228, v228 row_mirror row_mask:0xf bank_mask:0xf bound_ctrl:1
	v_add_f32_dpp v229, v229, v229 row_mirror row_mask:0xf bank_mask:0xf bound_ctrl:1
	v_add_f32_dpp v230, v230, v230 row_mirror row_mask:0xf bank_mask:0xf bound_ctrl:1
	v_add_f32_dpp v227, v227, v227 row_bcast:15 row_mask:0xa bank_mask:0xf
	v_add_f32_dpp v228, v228, v228 row_bcast:15 row_mask:0xa bank_mask:0xf
	v_add_f32_dpp v229, v229, v229 row_bcast:15 row_mask:0xa bank_mask:0xf
	v_add_f32_dpp v230, v230, v230 row_bcast:15 row_mask:0xa bank_mask:0xf
	v_add_f32_dpp v227, v227, v227 row_bcast:31 row_mask:0xc bank_mask:0xf
	v_add_f32_dpp v228, v228, v228 row_bcast:31 row_mask:0xc bank_mask:0xf
	v_add_f32_dpp v229, v229, v229 row_bcast:31 row_mask:0xc bank_mask:0xf
	v_add_f32_dpp v230, v230, v230 row_bcast:31 row_mask:0xc bank_mask:0xf
	v_readlane_b32 s0, v227, 63
	v_readlane_b32 s1, v228, 63
	v_readlane_b32 s33, v229, 63
	v_readlane_b32 s41, v230, 63
	v_mov_b32_e32 v231, s0
	v_mov_b32_e32 v234, s33
	v_sqrt_f32_e32 v231, v231
	v_mul_f32_e32 v235, s41, v210
	v_max_f32_e32 v231, 0x2b8cbccc, v231
	v_rcp_f32_e32 v231, v231
	v_cvt_pk_bf16_f32 v235, v235, v235
	v_mul_f32_e32 v213, v213, v231
	v_mul_f32_e32 v233, s1, v231
	v_mul_f32_e64 v217, -v213, v211
	v_mul_f32_e32 v211, v211, v206
	v_mul_f32_e32 v212, v212, v207
	v_mul_f32_e32 v216, v213, v133
	v_mul_f32_e32 v218, v211, v208
	v_fmac_f32_e32 v218, v233, v217
	ds_write2st64_b32 v222, v217, v218 offset0:7 offset1:8
	v_mul_f32_e32 v219, v216, v212
	v_mul_f32_e32 v220, v215, v212
	ds_write2st64_b32 v222, v211, v219 offset0:9 offset1:10
	ds_write_b32 v222, v220 offset:2816
	ds_write_b32 v223, v210 offset:1792
	ds_write_b32 v223, v234 offset:1800
	s_bitcmp1_b32 s72, 0
	s_cbranch_scc1 .Lrwq_nobv_1_p
	global_store_short v175, v235, s[6:7]
.Lrwq_nobv_1_p:
	s_add_u32 s6, s6, 0x5200
	s_addc_u32 s7, s7, 0
	v_mul_f32_e32 v204, 0xbfb8aa3b, v126
	v_mul_f32_e32 v205, 0x3fb8aa3b, v126
	v_sub_f32_e32 v208, v101, v102
	v_exp_f32_e32 v206, v204
	v_exp_f32_e32 v207, v205
	v_sub_f32_e32 v209, v109, v110
	v_sub_f32_e32 v210, v117, v118
	v_fma_f32 v208, v196, v208, v102
	v_fma_f32 v209, v197, v209, v110
	v_fma_f32 v210, v198, v210, v118
	v_mul_f32_e32 v213, v209, v199
	v_fma_f32 v214, v134, v200, v221
	v_mul_f32_e32 v215, v209, v214
	v_mul_f32_e32 v227, v213, v213
	v_mul_f32_e32 v228, v213, v134
	v_mul_f32_e32 v229, v215, v208
	v_mul_f32_e32 v228, v228, v208
	v_mul_f32_e32 v230, v229, v226
	v_add_f32_dpp v227, v227, v227 quad_perm:[1,0,3,2] row_mask:0xf bank_mask:0xf bound_ctrl:1
	v_add_f32_dpp v228, v228, v228 quad_perm:[1,0,3,2] row_mask:0xf bank_mask:0xf bound_ctrl:1
	v_add_f32_dpp v229, v229, v229 quad_perm:[1,0,3,2] row_mask:0xf bank_mask:0xf bound_ctrl:1
	v_add_f32_dpp v230, v230, v230 quad_perm:[1,0,3,2] row_mask:0xf bank_mask:0xf bound_ctrl:1
	v_add_f32_dpp v227, v227, v227 quad_perm:[2,3,0,1] row_mask:0xf bank_mask:0xf bound_ctrl:1
	v_add_f32_dpp v228, v228, v228 quad_perm:[2,3,0,1] row_mask:0xf bank_mask:0xf bound_ctrl:1
	v_add_f32_dpp v229, v229, v229 quad_perm:[2,3,0,1] row_mask:0xf bank_mask:0xf bound_ctrl:1
	v_add_f32_dpp v230, v230, v230 quad_perm:[2,3,0,1] row_mask:0xf bank_mask:0xf bound_ctrl:1
	v_add_f32_dpp v227, v227, v227 row_half_mirror row_mask:0xf bank_mask:0xf bound_ctrl:1
	v_add_f32_dpp v228, v228, v228 row_half_mirror row_mask:0xf bank_mask:0xf bound_ctrl:1
	v_add_f32_dpp v229, v229, v229 row_half_mirror row_mask:0xf bank_mask:0xf bound_ctrl:1
	v_add_f32_dpp v230, v230, v230 row_half_mirror row_mask:0xf bank_mask:0xf bound_ctrl:1
	v_add_f32_dpp v227, v227, v227 row_mirror row_mask:0xf bank_mask:0xf bound_ctrl:1
	v_add_f32_dpp v228, v228, v228 row_mirror row_mask:0xf bank_mask:0xf bound_ctrl:1
	v_add_f32_dpp v229, v229, v229 row_mirror row_mask:0xf bank_mask:0xf bound_ctrl:1
	v_add_f32_dpp v230, v230, v230 row_mirror row_mask:0xf bank_mask:0xf bound_ctrl:1
	v_add_f32_dpp v227, v227, v227 row_bcast:15 row_mask:0xa bank_mask:0xf
	v_add_f32_dpp v228, v228, v228 row_bcast:15 row_mask:0xa bank_mask:0xf
	v_add_f32_dpp v229, v229, v229 row_bcast:15 row_mask:0xa bank_mask:0xf
	v_add_f32_dpp v230, v230, v230 row_bcast:15 row_mask:0xa bank_mask:0xf
	v_add_f32_dpp v227, v227, v227 row_bcast:31 row_mask:0xc bank_mask:0xf
	v_add_f32_dpp v228, v228, v228 row_bcast:31 row_mask:0xc bank_mask:0xf
	v_add_f32_dpp v229, v229, v229 row_bcast:31 row_mask:0xc bank_mask:0xf
	v_add_f32_dpp v230, v230, v230 row_bcast:31 row_mask:0xc bank_mask:0xf
	v_readlane_b32 s0, v227, 63
	v_readlane_b32 s1, v228, 63
	v_readlane_b32 s33, v229, 63
	v_readlane_b32 s41, v230, 63
	v_mov_b32_e32 v231, s0
	v_mov_b32_e32 v234, s33
	v_sqrt_f32_e32 v231, v231
	v_mul_f32_e32 v235, s41, v210
	v_max_f32_e32 v231, 0x2b8cbccc, v231
	v_rcp_f32_e32 v231, v231
	v_cvt_pk_bf16_f32 v235, v235, v235
	v_mul_f32_e32 v213, v213, v231
	v_mul_f32_e32 v233, s1, v231
	v_mul_f32_e64 v217, -v213, v211
	v_mul_f32_e32 v211, v211, v206
	v_mul_f32_e32 v212, v212, v207
	v_mul_f32_e32 v216, v213, v134
	v_mul_f32_e32 v218, v211, v208
	v_fmac_f32_e32 v218, v233, v217
	ds_write2st64_b32 v222, v217, v218 offset0:14 offset1:15
	v_mul_f32_e32 v219, v216, v212
	v_mul_f32_e32 v220, v215, v212
	ds_write2st64_b32 v222, v211, v219 offset0:16 offset1:17
	ds_write_b32 v222, v220 offset:4608
	ds_write_b32 v223, v210 offset:3584
	ds_write_b32 v223, v234 offset:3592
	s_bitcmp1_b32 s72, 0
	s_cbranch_scc1 .Lrwq_nobv_2_p
	global_store_short v175, v235, s[6:7]
.Lrwq_nobv_2_p:
	s_add_u32 s6, s6, 0x5200
	s_addc_u32 s7, s7, 0
	v_mul_f32_e32 v204, 0xbfb8aa3b, v127
	v_mul_f32_e32 v205, 0x3fb8aa3b, v127
	v_sub_f32_e32 v208, v102, v103
	v_exp_f32_e32 v206, v204
	v_exp_f32_e32 v207, v205
	v_sub_f32_e32 v209, v110, v111
	v_sub_f32_e32 v210, v118, v119
	v_fma_f32 v208, v196, v208, v103
	v_fma_f32 v209, v197, v209, v111
	v_fma_f32 v210, v198, v210, v119
	v_mul_f32_e32 v213, v209, v199
	v_fma_f32 v214, v135, v200, v221
	v_mul_f32_e32 v215, v209, v214
	v_mul_f32_e32 v227, v213, v213
	v_mul_f32_e32 v228, v213, v135
	v_mul_f32_e32 v229, v215, v208
	v_mul_f32_e32 v228, v228, v208
	v_mul_f32_e32 v230, v229, v226
	v_add_f32_dpp v227, v227, v227 quad_perm:[1,0,3,2] row_mask:0xf bank_mask:0xf bound_ctrl:1
	v_add_f32_dpp v228, v228, v228 quad_perm:[1,0,3,2] row_mask:0xf bank_mask:0xf bound_ctrl:1
	v_add_f32_dpp v229, v229, v229 quad_perm:[1,0,3,2] row_mask:0xf bank_mask:0xf bound_ctrl:1
	v_add_f32_dpp v230, v230, v230 quad_perm:[1,0,3,2] row_mask:0xf bank_mask:0xf bound_ctrl:1
	v_add_f32_dpp v227, v227, v227 quad_perm:[2,3,0,1] row_mask:0xf bank_mask:0xf bound_ctrl:1
	v_add_f32_dpp v228, v228, v228 quad_perm:[2,3,0,1] row_mask:0xf bank_mask:0xf bound_ctrl:1
	v_add_f32_dpp v229, v229, v229 quad_perm:[2,3,0,1] row_mask:0xf bank_mask:0xf bound_ctrl:1
	v_add_f32_dpp v230, v230, v230 quad_perm:[2,3,0,1] row_mask:0xf bank_mask:0xf bound_ctrl:1
	v_add_f32_dpp v227, v227, v227 row_half_mirror row_mask:0xf bank_mask:0xf bound_ctrl:1
	v_add_f32_dpp v228, v228, v228 row_half_mirror row_mask:0xf bank_mask:0xf bound_ctrl:1
	v_add_f32_dpp v229, v229, v229 row_half_mirror row_mask:0xf bank_mask:0xf bound_ctrl:1
	v_add_f32_dpp v230, v230, v230 row_half_mirror row_mask:0xf bank_mask:0xf bound_ctrl:1
	v_add_f32_dpp v227, v227, v227 row_mirror row_mask:0xf bank_mask:0xf bound_ctrl:1
	v_add_f32_dpp v228, v228, v228 row_mirror row_mask:0xf bank_mask:0xf bound_ctrl:1
	v_add_f32_dpp v229, v229, v229 row_mirror row_mask:0xf bank_mask:0xf bound_ctrl:1
	v_add_f32_dpp v230, v230, v230 row_mirror row_mask:0xf bank_mask:0xf bound_ctrl:1
	v_add_f32_dpp v227, v227, v227 row_bcast:15 row_mask:0xa bank_mask:0xf
	v_add_f32_dpp v228, v228, v228 row_bcast:15 row_mask:0xa bank_mask:0xf
	v_add_f32_dpp v229, v229, v229 row_bcast:15 row_mask:0xa bank_mask:0xf
	v_add_f32_dpp v230, v230, v230 row_bcast:15 row_mask:0xa bank_mask:0xf
	v_add_f32_dpp v227, v227, v227 row_bcast:31 row_mask:0xc bank_mask:0xf
	v_add_f32_dpp v228, v228, v228 row_bcast:31 row_mask:0xc bank_mask:0xf
	v_add_f32_dpp v229, v229, v229 row_bcast:31 row_mask:0xc bank_mask:0xf
	v_add_f32_dpp v230, v230, v230 row_bcast:31 row_mask:0xc bank_mask:0xf
	v_readlane_b32 s0, v227, 63
	v_readlane_b32 s1, v228, 63
	v_readlane_b32 s33, v229, 63
	v_readlane_b32 s41, v230, 63
	v_mov_b32_e32 v231, s0
	v_mov_b32_e32 v234, s33
	v_sqrt_f32_e32 v231, v231
	v_mul_f32_e32 v235, s41, v210
	v_max_f32_e32 v231, 0x2b8cbccc, v231
	v_rcp_f32_e32 v231, v231
	v_cvt_pk_bf16_f32 v235, v235, v235
	v_mul_f32_e32 v213, v213, v231
	v_mul_f32_e32 v233, s1, v231
	v_mul_f32_e64 v217, -v213, v211
	v_mul_f32_e32 v211, v211, v206
	v_mul_f32_e32 v212, v212, v207
	v_mul_f32_e32 v216, v213, v135
	v_mul_f32_e32 v218, v211, v208
	v_fmac_f32_e32 v218, v233, v217
	ds_write2st64_b32 v222, v217, v218 offset0:21 offset1:22
	v_mul_f32_e32 v219, v216, v212
	v_mul_f32_e32 v220, v215, v212
	ds_write2st64_b32 v222, v211, v219 offset0:23 offset1:24
	ds_write_b32 v222, v220 offset:6400
	ds_write_b32 v223, v210 offset:5376
	ds_write_b32 v223, v234 offset:5384
	s_bitcmp1_b32 s72, 0
	s_cbranch_scc1 .Lrwq_nobv_3_p
	global_store_short v175, v235, s[6:7]
.Lrwq_nobv_3_p:
	s_add_u32 s6, s6, 0x5200
	s_addc_u32 s7, s7, 0
	v_mul_f32_e32 v204, 0xbfb8aa3b, v128
	v_mul_f32_e32 v205, 0x3fb8aa3b, v128
	v_sub_f32_e32 v208, v103, v104
	v_exp_f32_e32 v206, v204
	v_exp_f32_e32 v207, v205
	v_sub_f32_e32 v209, v111, v112
	v_sub_f32_e32 v210, v119, v120
	v_fma_f32 v208, v196, v208, v104
	v_fma_f32 v209, v197, v209, v112
	v_fma_f32 v210, v198, v210, v120
	v_mul_f32_e32 v213, v209, v199
	v_fma_f32 v214, v136, v200, v221
	v_mul_f32_e32 v215, v209, v214
	v_mul_f32_e32 v227, v213, v213
	v_mul_f32_e32 v228, v213, v136
	v_mul_f32_e32 v229, v215, v208
	v_mul_f32_e32 v228, v228, v208
	v_mul_f32_e32 v230, v229, v226
	v_add_f32_dpp v227, v227, v227 quad_perm:[1,0,3,2] row_mask:0xf bank_mask:0xf bound_ctrl:1
	v_add_f32_dpp v228, v228, v228 quad_perm:[1,0,3,2] row_mask:0xf bank_mask:0xf bound_ctrl:1
	v_add_f32_dpp v229, v229, v229 quad_perm:[1,0,3,2] row_mask:0xf bank_mask:0xf bound_ctrl:1
	v_add_f32_dpp v230, v230, v230 quad_perm:[1,0,3,2] row_mask:0xf bank_mask:0xf bound_ctrl:1
	v_add_f32_dpp v227, v227, v227 quad_perm:[2,3,0,1] row_mask:0xf bank_mask:0xf bound_ctrl:1
	v_add_f32_dpp v228, v228, v228 quad_perm:[2,3,0,1] row_mask:0xf bank_mask:0xf bound_ctrl:1
	v_add_f32_dpp v229, v229, v229 quad_perm:[2,3,0,1] row_mask:0xf bank_mask:0xf bound_ctrl:1
	v_add_f32_dpp v230, v230, v230 quad_perm:[2,3,0,1] row_mask:0xf bank_mask:0xf bound_ctrl:1
	v_add_f32_dpp v227, v227, v227 row_half_mirror row_mask:0xf bank_mask:0xf bound_ctrl:1
	v_add_f32_dpp v228, v228, v228 row_half_mirror row_mask:0xf bank_mask:0xf bound_ctrl:1
	v_add_f32_dpp v229, v229, v229 row_half_mirror row_mask:0xf bank_mask:0xf bound_ctrl:1
	v_add_f32_dpp v230, v230, v230 row_half_mirror row_mask:0xf bank_mask:0xf bound_ctrl:1
	v_add_f32_dpp v227, v227, v227 row_mirror row_mask:0xf bank_mask:0xf bound_ctrl:1
	v_add_f32_dpp v228, v228, v228 row_mirror row_mask:0xf bank_mask:0xf bound_ctrl:1
	v_add_f32_dpp v229, v229, v229 row_mirror row_mask:0xf bank_mask:0xf bound_ctrl:1
	v_add_f32_dpp v230, v230, v230 row_mirror row_mask:0xf bank_mask:0xf bound_ctrl:1
	v_add_f32_dpp v227, v227, v227 row_bcast:15 row_mask:0xa bank_mask:0xf
	v_add_f32_dpp v228, v228, v228 row_bcast:15 row_mask:0xa bank_mask:0xf
	v_add_f32_dpp v229, v229, v229 row_bcast:15 row_mask:0xa bank_mask:0xf
	v_add_f32_dpp v230, v230, v230 row_bcast:15 row_mask:0xa bank_mask:0xf
	v_add_f32_dpp v227, v227, v227 row_bcast:31 row_mask:0xc bank_mask:0xf
	v_add_f32_dpp v228, v228, v228 row_bcast:31 row_mask:0xc bank_mask:0xf
	v_add_f32_dpp v229, v229, v229 row_bcast:31 row_mask:0xc bank_mask:0xf
	v_add_f32_dpp v230, v230, v230 row_bcast:31 row_mask:0xc bank_mask:0xf
	v_readlane_b32 s0, v227, 63
	v_readlane_b32 s1, v228, 63
	v_readlane_b32 s33, v229, 63
	v_readlane_b32 s41, v230, 63
	v_mov_b32_e32 v231, s0
	v_mov_b32_e32 v234, s33
	v_sqrt_f32_e32 v231, v231
	v_mul_f32_e32 v235, s41, v210
	v_max_f32_e32 v231, 0x2b8cbccc, v231
	v_rcp_f32_e32 v231, v231
	v_cvt_pk_bf16_f32 v235, v235, v235
	v_mul_f32_e32 v213, v213, v231
	v_mul_f32_e32 v233, s1, v231
	v_mul_f32_e64 v217, -v213, v211
	v_mul_f32_e32 v211, v211, v206
	v_mul_f32_e32 v212, v212, v207
	v_mul_f32_e32 v216, v213, v136
	v_mul_f32_e32 v218, v211, v208
	v_fmac_f32_e32 v218, v233, v217
	ds_write2st64_b32 v222, v217, v218 offset0:28 offset1:29
	v_mul_f32_e32 v219, v216, v212
	v_mul_f32_e32 v220, v215, v212
	ds_write2st64_b32 v222, v211, v219 offset0:30 offset1:31
	ds_write_b32 v222, v220 offset:8192
	ds_write_b32 v223, v210 offset:7168
	ds_write_b32 v223, v234 offset:7176
	s_bitcmp1_b32 s72, 0
	s_cbranch_scc1 .Lrwq_nobv_4_p
	global_store_short v175, v235, s[6:7]
.Lrwq_nobv_4_p:
	s_add_u32 s6, s6, 0x5200
	s_addc_u32 s7, s7, 0
	v_mul_f32_e32 v204, 0xbfb8aa3b, v129
	v_mul_f32_e32 v205, 0x3fb8aa3b, v129
	v_sub_f32_e32 v208, v104, v105
	v_exp_f32_e32 v206, v204
	v_exp_f32_e32 v207, v205
	v_sub_f32_e32 v209, v112, v113
	v_sub_f32_e32 v210, v120, v121
	v_fma_f32 v208, v196, v208, v105
	v_fma_f32 v209, v197, v209, v113
	v_fma_f32 v210, v198, v210, v121
	v_mul_f32_e32 v213, v209, v199
	v_fma_f32 v214, v137, v200, v221
	v_mul_f32_e32 v215, v209, v214
	v_mul_f32_e32 v227, v213, v213
	v_mul_f32_e32 v228, v213, v137
	v_mul_f32_e32 v229, v215, v208
	v_mul_f32_e32 v228, v228, v208
	v_mul_f32_e32 v230, v229, v226
	v_add_f32_dpp v227, v227, v227 quad_perm:[1,0,3,2] row_mask:0xf bank_mask:0xf bound_ctrl:1
	v_add_f32_dpp v228, v228, v228 quad_perm:[1,0,3,2] row_mask:0xf bank_mask:0xf bound_ctrl:1
	v_add_f32_dpp v229, v229, v229 quad_perm:[1,0,3,2] row_mask:0xf bank_mask:0xf bound_ctrl:1
	v_add_f32_dpp v230, v230, v230 quad_perm:[1,0,3,2] row_mask:0xf bank_mask:0xf bound_ctrl:1
	v_add_f32_dpp v227, v227, v227 quad_perm:[2,3,0,1] row_mask:0xf bank_mask:0xf bound_ctrl:1
	v_add_f32_dpp v228, v228, v228 quad_perm:[2,3,0,1] row_mask:0xf bank_mask:0xf bound_ctrl:1
	v_add_f32_dpp v229, v229, v229 quad_perm:[2,3,0,1] row_mask:0xf bank_mask:0xf bound_ctrl:1
	v_add_f32_dpp v230, v230, v230 quad_perm:[2,3,0,1] row_mask:0xf bank_mask:0xf bound_ctrl:1
	v_add_f32_dpp v227, v227, v227 row_half_mirror row_mask:0xf bank_mask:0xf bound_ctrl:1
	v_add_f32_dpp v228, v228, v228 row_half_mirror row_mask:0xf bank_mask:0xf bound_ctrl:1
	v_add_f32_dpp v229, v229, v229 row_half_mirror row_mask:0xf bank_mask:0xf bound_ctrl:1
	v_add_f32_dpp v230, v230, v230 row_half_mirror row_mask:0xf bank_mask:0xf bound_ctrl:1
	v_add_f32_dpp v227, v227, v227 row_mirror row_mask:0xf bank_mask:0xf bound_ctrl:1
	v_add_f32_dpp v228, v228, v228 row_mirror row_mask:0xf bank_mask:0xf bound_ctrl:1
	v_add_f32_dpp v229, v229, v229 row_mirror row_mask:0xf bank_mask:0xf bound_ctrl:1
	v_add_f32_dpp v230, v230, v230 row_mirror row_mask:0xf bank_mask:0xf bound_ctrl:1
	v_add_f32_dpp v227, v227, v227 row_bcast:15 row_mask:0xa bank_mask:0xf
	v_add_f32_dpp v228, v228, v228 row_bcast:15 row_mask:0xa bank_mask:0xf
	v_add_f32_dpp v229, v229, v229 row_bcast:15 row_mask:0xa bank_mask:0xf
	v_add_f32_dpp v230, v230, v230 row_bcast:15 row_mask:0xa bank_mask:0xf
	v_add_f32_dpp v227, v227, v227 row_bcast:31 row_mask:0xc bank_mask:0xf
	v_add_f32_dpp v228, v228, v228 row_bcast:31 row_mask:0xc bank_mask:0xf
	v_add_f32_dpp v229, v229, v229 row_bcast:31 row_mask:0xc bank_mask:0xf
	v_add_f32_dpp v230, v230, v230 row_bcast:31 row_mask:0xc bank_mask:0xf
	v_readlane_b32 s0, v227, 63
	v_readlane_b32 s1, v228, 63
	v_readlane_b32 s33, v229, 63
	v_readlane_b32 s41, v230, 63
	v_mov_b32_e32 v231, s0
	v_mov_b32_e32 v234, s33
	v_sqrt_f32_e32 v231, v231
	v_mul_f32_e32 v235, s41, v210
	v_max_f32_e32 v231, 0x2b8cbccc, v231
	v_rcp_f32_e32 v231, v231
	v_cvt_pk_bf16_f32 v235, v235, v235
	v_mul_f32_e32 v213, v213, v231
	v_mul_f32_e32 v233, s1, v231
	v_mul_f32_e64 v217, -v213, v211
	v_mul_f32_e32 v211, v211, v206
	v_mul_f32_e32 v212, v212, v207
	v_mul_f32_e32 v216, v213, v137
	v_mul_f32_e32 v218, v211, v208
	v_fmac_f32_e32 v218, v233, v217
	ds_write2st64_b32 v222, v217, v218 offset0:35 offset1:36
	v_mul_f32_e32 v219, v216, v212
	v_mul_f32_e32 v220, v215, v212
	ds_write2st64_b32 v222, v211, v219 offset0:37 offset1:38
	ds_write_b32 v222, v220 offset:9984
	ds_write_b32 v223, v210 offset:8960
	ds_write_b32 v223, v234 offset:8968
	s_bitcmp1_b32 s72, 0
	s_cbranch_scc1 .Lrwq_nobv_5_p
	global_store_short v175, v235, s[6:7]
.Lrwq_nobv_5_p:
	s_add_u32 s6, s6, 0x5200
	s_addc_u32 s7, s7, 0
	v_mul_f32_e32 v204, 0xbfb8aa3b, v130
	v_mul_f32_e32 v205, 0x3fb8aa3b, v130
	v_sub_f32_e32 v208, v105, v106
	v_exp_f32_e32 v206, v204
	v_exp_f32_e32 v207, v205
	v_sub_f32_e32 v209, v113, v114
	v_sub_f32_e32 v210, v121, v122
	v_fma_f32 v208, v196, v208, v106
	v_fma_f32 v209, v197, v209, v114
	v_fma_f32 v210, v198, v210, v122
	v_mul_f32_e32 v213, v209, v199
	v_fma_f32 v214, v138, v200, v221
	v_mul_f32_e32 v215, v209, v214
	v_mul_f32_e32 v227, v213, v213
	v_mul_f32_e32 v228, v213, v138
	v_mul_f32_e32 v229, v215, v208
	v_mul_f32_e32 v228, v228, v208
	v_mul_f32_e32 v230, v229, v226
	v_add_f32_dpp v227, v227, v227 quad_perm:[1,0,3,2] row_mask:0xf bank_mask:0xf bound_ctrl:1
	v_add_f32_dpp v228, v228, v228 quad_perm:[1,0,3,2] row_mask:0xf bank_mask:0xf bound_ctrl:1
	v_add_f32_dpp v229, v229, v229 quad_perm:[1,0,3,2] row_mask:0xf bank_mask:0xf bound_ctrl:1
	v_add_f32_dpp v230, v230, v230 quad_perm:[1,0,3,2] row_mask:0xf bank_mask:0xf bound_ctrl:1
	v_add_f32_dpp v227, v227, v227 quad_perm:[2,3,0,1] row_mask:0xf bank_mask:0xf bound_ctrl:1
	v_add_f32_dpp v228, v228, v228 quad_perm:[2,3,0,1] row_mask:0xf bank_mask:0xf bound_ctrl:1
	v_add_f32_dpp v229, v229, v229 quad_perm:[2,3,0,1] row_mask:0xf bank_mask:0xf bound_ctrl:1
	v_add_f32_dpp v230, v230, v230 quad_perm:[2,3,0,1] row_mask:0xf bank_mask:0xf bound_ctrl:1
	v_add_f32_dpp v227, v227, v227 row_half_mirror row_mask:0xf bank_mask:0xf bound_ctrl:1
	v_add_f32_dpp v228, v228, v228 row_half_mirror row_mask:0xf bank_mask:0xf bound_ctrl:1
	v_add_f32_dpp v229, v229, v229 row_half_mirror row_mask:0xf bank_mask:0xf bound_ctrl:1
	v_add_f32_dpp v230, v230, v230 row_half_mirror row_mask:0xf bank_mask:0xf bound_ctrl:1
	v_add_f32_dpp v227, v227, v227 row_mirror row_mask:0xf bank_mask:0xf bound_ctrl:1
	v_add_f32_dpp v228, v228, v228 row_mirror row_mask:0xf bank_mask:0xf bound_ctrl:1
	v_add_f32_dpp v229, v229, v229 row_mirror row_mask:0xf bank_mask:0xf bound_ctrl:1
	v_add_f32_dpp v230, v230, v230 row_mirror row_mask:0xf bank_mask:0xf bound_ctrl:1
	v_add_f32_dpp v227, v227, v227 row_bcast:15 row_mask:0xa bank_mask:0xf
	v_add_f32_dpp v228, v228, v228 row_bcast:15 row_mask:0xa bank_mask:0xf
	v_add_f32_dpp v229, v229, v229 row_bcast:15 row_mask:0xa bank_mask:0xf
	v_add_f32_dpp v230, v230, v230 row_bcast:15 row_mask:0xa bank_mask:0xf
	v_add_f32_dpp v227, v227, v227 row_bcast:31 row_mask:0xc bank_mask:0xf
	v_add_f32_dpp v228, v228, v228 row_bcast:31 row_mask:0xc bank_mask:0xf
	v_add_f32_dpp v229, v229, v229 row_bcast:31 row_mask:0xc bank_mask:0xf
	v_add_f32_dpp v230, v230, v230 row_bcast:31 row_mask:0xc bank_mask:0xf
	v_readlane_b32 s0, v227, 63
	v_readlane_b32 s1, v228, 63
	v_readlane_b32 s33, v229, 63
	v_readlane_b32 s41, v230, 63
	v_mov_b32_e32 v231, s0
	v_mov_b32_e32 v234, s33
	v_sqrt_f32_e32 v231, v231
	v_mul_f32_e32 v235, s41, v210
	v_max_f32_e32 v231, 0x2b8cbccc, v231
	v_rcp_f32_e32 v231, v231
	v_cvt_pk_bf16_f32 v235, v235, v235
	v_mul_f32_e32 v213, v213, v231
	v_mul_f32_e32 v233, s1, v231
	v_mul_f32_e64 v217, -v213, v211
	v_mul_f32_e32 v211, v211, v206
	v_mul_f32_e32 v212, v212, v207
	v_mul_f32_e32 v216, v213, v138
	v_mul_f32_e32 v218, v211, v208
	v_fmac_f32_e32 v218, v233, v217
	ds_write2st64_b32 v222, v217, v218 offset0:42 offset1:43
	v_mul_f32_e32 v219, v216, v212
	v_mul_f32_e32 v220, v215, v212
	ds_write2st64_b32 v222, v211, v219 offset0:44 offset1:45
	ds_write_b32 v222, v220 offset:11776
	ds_write_b32 v223, v210 offset:10752
	ds_write_b32 v223, v234 offset:10760
	s_bitcmp1_b32 s72, 0
	s_cbranch_scc1 .Lrwq_nobv_6_p
	global_store_short v175, v235, s[6:7]
.Lrwq_nobv_6_p:
	s_add_u32 s6, s6, 0x5200
	s_addc_u32 s7, s7, 0
	v_mul_f32_e32 v204, 0xbfb8aa3b, v131
	v_mul_f32_e32 v205, 0x3fb8aa3b, v131
	v_sub_f32_e32 v208, v106, v107
	v_exp_f32_e32 v206, v204
	v_exp_f32_e32 v207, v205
	v_sub_f32_e32 v209, v114, v115
	v_sub_f32_e32 v210, v122, v123
	v_fma_f32 v208, v196, v208, v107
	v_fma_f32 v209, v197, v209, v115
	v_fma_f32 v210, v198, v210, v123
	v_mul_f32_e32 v213, v209, v199
	v_fma_f32 v214, v139, v200, v221
	v_mul_f32_e32 v215, v209, v214
	v_mul_f32_e32 v227, v213, v213
	v_mul_f32_e32 v228, v213, v139
	v_mul_f32_e32 v229, v215, v208
	v_mul_f32_e32 v228, v228, v208
	v_mul_f32_e32 v230, v229, v226
	v_add_f32_dpp v227, v227, v227 quad_perm:[1,0,3,2] row_mask:0xf bank_mask:0xf bound_ctrl:1
	v_add_f32_dpp v228, v228, v228 quad_perm:[1,0,3,2] row_mask:0xf bank_mask:0xf bound_ctrl:1
	v_add_f32_dpp v229, v229, v229 quad_perm:[1,0,3,2] row_mask:0xf bank_mask:0xf bound_ctrl:1
	v_add_f32_dpp v230, v230, v230 quad_perm:[1,0,3,2] row_mask:0xf bank_mask:0xf bound_ctrl:1
	v_add_f32_dpp v227, v227, v227 quad_perm:[2,3,0,1] row_mask:0xf bank_mask:0xf bound_ctrl:1
	v_add_f32_dpp v228, v228, v228 quad_perm:[2,3,0,1] row_mask:0xf bank_mask:0xf bound_ctrl:1
	v_add_f32_dpp v229, v229, v229 quad_perm:[2,3,0,1] row_mask:0xf bank_mask:0xf bound_ctrl:1
	v_add_f32_dpp v230, v230, v230 quad_perm:[2,3,0,1] row_mask:0xf bank_mask:0xf bound_ctrl:1
	v_add_f32_dpp v227, v227, v227 row_half_mirror row_mask:0xf bank_mask:0xf bound_ctrl:1
	v_add_f32_dpp v228, v228, v228 row_half_mirror row_mask:0xf bank_mask:0xf bound_ctrl:1
	v_add_f32_dpp v229, v229, v229 row_half_mirror row_mask:0xf bank_mask:0xf bound_ctrl:1
	v_add_f32_dpp v230, v230, v230 row_half_mirror row_mask:0xf bank_mask:0xf bound_ctrl:1
	v_add_f32_dpp v227, v227, v227 row_mirror row_mask:0xf bank_mask:0xf bound_ctrl:1
	v_add_f32_dpp v228, v228, v228 row_mirror row_mask:0xf bank_mask:0xf bound_ctrl:1
	v_add_f32_dpp v229, v229, v229 row_mirror row_mask:0xf bank_mask:0xf bound_ctrl:1
	v_add_f32_dpp v230, v230, v230 row_mirror row_mask:0xf bank_mask:0xf bound_ctrl:1
	v_add_f32_dpp v227, v227, v227 row_bcast:15 row_mask:0xa bank_mask:0xf
	v_add_f32_dpp v228, v228, v228 row_bcast:15 row_mask:0xa bank_mask:0xf
	v_add_f32_dpp v229, v229, v229 row_bcast:15 row_mask:0xa bank_mask:0xf
	v_add_f32_dpp v230, v230, v230 row_bcast:15 row_mask:0xa bank_mask:0xf
	v_add_f32_dpp v227, v227, v227 row_bcast:31 row_mask:0xc bank_mask:0xf
	v_add_f32_dpp v228, v228, v228 row_bcast:31 row_mask:0xc bank_mask:0xf
	v_add_f32_dpp v229, v229, v229 row_bcast:31 row_mask:0xc bank_mask:0xf
	v_add_f32_dpp v230, v230, v230 row_bcast:31 row_mask:0xc bank_mask:0xf
	v_readlane_b32 s0, v227, 63
	v_readlane_b32 s1, v228, 63
	v_readlane_b32 s33, v229, 63
	v_readlane_b32 s41, v230, 63
	v_mov_b32_e32 v231, s0
	v_mov_b32_e32 v234, s33
	v_sqrt_f32_e32 v231, v231
	v_mul_f32_e32 v235, s41, v210
	v_max_f32_e32 v231, 0x2b8cbccc, v231
	v_rcp_f32_e32 v231, v231
	v_cvt_pk_bf16_f32 v235, v235, v235
	v_mul_f32_e32 v213, v213, v231
	v_mul_f32_e32 v233, s1, v231
	v_mul_f32_e64 v217, -v213, v211
	v_mul_f32_e32 v211, v211, v206
	v_mul_f32_e32 v212, v212, v207
	v_mul_f32_e32 v216, v213, v139
	v_mul_f32_e32 v218, v211, v208
	v_fmac_f32_e32 v218, v233, v217
	ds_write2st64_b32 v222, v217, v218 offset0:49 offset1:50
	v_mul_f32_e32 v219, v216, v212
	v_mul_f32_e32 v220, v215, v212
	ds_write2st64_b32 v222, v211, v219 offset0:51 offset1:52
	ds_write_b32 v222, v220 offset:13568
	ds_write_b32 v223, v210 offset:12544
	ds_write_b32 v223, v234 offset:12552
	s_bitcmp1_b32 s72, 0
	s_cbranch_scc1 .Lrwq_nobv_7_p
	global_store_short v175, v235, s[6:7]
.Lrwq_nobv_7_p:
	s_add_u32 s14, s14, 0xa4000
	s_addc_u32 s15, s15, 0
	s_sub_u32 s0, s98, 0x5200
	s_subb_u32 s1, s99, 0
	global_load_short_d16_hi v172, v175, s[0:1] offset:-2048
	global_load_short_d16_hi v173, v175, s[0:1]
	global_load_short_d16_hi v174, v175, s[0:1] offset:2048
	s_add_u32 s0, s0, 0x5200
	s_addc_u32 s1, s1, 0
	global_load_short_d16_hi v100, v175, s[0:1] offset:-2048
	global_load_short_d16_hi v108, v175, s[0:1]
	global_load_short_d16_hi v116, v175, s[0:1] offset:2048
	s_add_u32 s0, s0, 0x5200
	s_addc_u32 s1, s1, 0
	global_load_short_d16_hi v101, v175, s[0:1] offset:-2048
	global_load_short_d16_hi v109, v175, s[0:1]
	global_load_short_d16_hi v117, v175, s[0:1] offset:2048
	s_add_u32 s0, s0, 0x5200
	s_addc_u32 s1, s1, 0
	global_load_short_d16_hi v102, v175, s[0:1] offset:-2048
	global_load_short_d16_hi v110, v175, s[0:1]
	global_load_short_d16_hi v118, v175, s[0:1] offset:2048
	s_add_u32 s0, s0, 0x5200
	s_addc_u32 s1, s1, 0
	global_load_short_d16_hi v103, v175, s[0:1] offset:-2048
	global_load_short_d16_hi v111, v175, s[0:1]
	global_load_short_d16_hi v119, v175, s[0:1] offset:2048
	s_add_u32 s0, s0, 0x5200
	s_addc_u32 s1, s1, 0
	global_load_short_d16_hi v104, v175, s[0:1] offset:-2048
	global_load_short_d16_hi v112, v175, s[0:1]
	global_load_short_d16_hi v120, v175, s[0:1] offset:2048
	s_add_u32 s0, s0, 0x5200
	s_addc_u32 s1, s1, 0
	global_load_short_d16_hi v105, v175, s[0:1] offset:-2048
	global_load_short_d16_hi v113, v175, s[0:1]
	global_load_short_d16_hi v121, v175, s[0:1] offset:2048
	s_add_u32 s0, s0, 0x5200
	s_addc_u32 s1, s1, 0
	global_load_short_d16_hi v106, v175, s[0:1] offset:-2048
	global_load_short_d16_hi v114, v175, s[0:1]
	global_load_short_d16_hi v122, v175, s[0:1] offset:2048
	s_add_u32 s0, s0, 0x5200
	s_addc_u32 s1, s1, 0
	global_load_short_d16_hi v107, v175, s[0:1] offset:-2048
	global_load_short_d16_hi v115, v175, s[0:1]
	global_load_short_d16_hi v123, v175, s[0:1] offset:2048
	s_add_u32 s0, s100, 0x0
	s_addc_u32 s1, s101, 0
	global_load_short_d16_hi v124, v175, s[0:1]
	global_load_short_d16_hi v125, v175, s[0:1] offset:2048
	s_add_u32 s0, s58, 0x0
	s_addc_u32 s1, s59, 0
	global_load_short_d16_hi v132, v175, s[0:1]
	global_load_short_d16_hi v133, v175, s[0:1] offset:2048
	s_add_u32 s0, s100, 0x1000
	s_addc_u32 s1, s101, 0
	global_load_short_d16_hi v126, v175, s[0:1]
	global_load_short_d16_hi v127, v175, s[0:1] offset:2048
	s_add_u32 s0, s58, 0x1000
	s_addc_u32 s1, s59, 0
	global_load_short_d16_hi v134, v175, s[0:1]
	global_load_short_d16_hi v135, v175, s[0:1] offset:2048
	s_add_u32 s0, s100, 0x2000
	s_addc_u32 s1, s101, 0
	global_load_short_d16_hi v128, v175, s[0:1]
	global_load_short_d16_hi v129, v175, s[0:1] offset:2048
	s_add_u32 s0, s58, 0x2000
	s_addc_u32 s1, s59, 0
	global_load_short_d16_hi v136, v175, s[0:1]
	global_load_short_d16_hi v137, v175, s[0:1] offset:2048
	s_add_u32 s0, s100, 0x3000
	s_addc_u32 s1, s101, 0
	global_load_short_d16_hi v130, v175, s[0:1]
	global_load_short_d16_hi v131, v175, s[0:1] offset:2048
	s_add_u32 s0, s58, 0x3000
	s_addc_u32 s1, s59, 0
	global_load_short_d16_hi v138, v175, s[0:1]
	global_load_short_d16_hi v139, v175, s[0:1] offset:2048
	s_add_u32 s98, s98, 0xa4000
	s_addc_u32 s99, s99, 0
	s_add_u32 s100, s100, 0x10000
	s_addc_u32 s101, s101, 0
	s_add_u32 s58, s58, 0x10000
	s_addc_u32 s59, s59, 0

.LBB0_1348:
	s_and_saveexec_b64 s[0:1], s[16:17]
	s_xor_b64 s[56:57], exec, s[0:1]
	s_cbranch_execz .LBB0_1368
	s_cmp_eq_u32 s30, 63
	s_cbranch_scc1 .LBB0_1368
	s_andn2_b32 s0, 1, s30
	s_mul_i32 s0, s0, 0xe000
	s_waitcnt vmcnt(0)
	v_add_u32_e32 v222, s0, v224
	v_add_u32_e32 v223, s0, v225
	s_mov_b64 s[6:7], s[14:15]
	v_mul_f32_e32 v204, 0xbfb8aa3b, v124
	v_mul_f32_e32 v205, 0x3fb8aa3b, v124
	v_sub_f32_e32 v208, v172, v100
	v_exp_f32_e32 v211, v204
	v_exp_f32_e32 v212, v205
	v_sub_f32_e32 v209, v173, v108
	v_sub_f32_e32 v210, v174, v116
	v_fma_f32 v208, v196, v208, v100
	v_fma_f32 v209, v197, v209, v108
	v_fma_f32 v210, v198, v210, v116
	v_mul_f32_e32 v213, v209, v199
	v_fma_f32 v214, v132, v200, v221
	v_mul_f32_e32 v215, v209, v214
	v_mul_f32_e32 v227, v213, v213
	v_mul_f32_e32 v228, v213, v132
	v_mul_f32_e32 v229, v215, v208
	v_mul_f32_e32 v228, v228, v208
	v_mul_f32_e32 v230, v229, v226
	v_add_f32_dpp v227, v227, v227 quad_perm:[1,0,3,2] row_mask:0xf bank_mask:0xf bound_ctrl:1
	v_add_f32_dpp v228, v228, v228 quad_perm:[1,0,3,2] row_mask:0xf bank_mask:0xf bound_ctrl:1
	v_add_f32_dpp v229, v229, v229 quad_perm:[1,0,3,2] row_mask:0xf bank_mask:0xf bound_ctrl:1
	v_add_f32_dpp v230, v230, v230 quad_perm:[1,0,3,2] row_mask:0xf bank_mask:0xf bound_ctrl:1
	v_add_f32_dpp v227, v227, v227 quad_perm:[2,3,0,1] row_mask:0xf bank_mask:0xf bound_ctrl:1
	v_add_f32_dpp v228, v228, v228 quad_perm:[2,3,0,1] row_mask:0xf bank_mask:0xf bound_ctrl:1
	v_add_f32_dpp v229, v229, v229 quad_perm:[2,3,0,1] row_mask:0xf bank_mask:0xf bound_ctrl:1
	v_add_f32_dpp v230, v230, v230 quad_perm:[2,3,0,1] row_mask:0xf bank_mask:0xf bound_ctrl:1
	v_add_f32_dpp v227, v227, v227 row_half_mirror row_mask:0xf bank_mask:0xf bound_ctrl:1
	v_add_f32_dpp v228, v228, v228 row_half_mirror row_mask:0xf bank_mask:0xf bound_ctrl:1
	v_add_f32_dpp v229, v229, v229 row_half_mirror row_mask:0xf bank_mask:0xf bound_ctrl:1
	v_add_f32_dpp v230, v230, v230 row_half_mirror row_mask:0xf bank_mask:0xf bound_ctrl:1
	v_add_f32_dpp v227, v227, v227 row_mirror row_mask:0xf bank_mask:0xf bound_ctrl:1
	v_add_f32_dpp v228, v228, v228 row_mirror row_mask:0xf bank_mask:0xf bound_ctrl:1
	v_add_f32_dpp v229, v229, v229 row_mirror row_mask:0xf bank_mask:0xf bound_ctrl:1
	v_add_f32_dpp v230, v230, v230 row_mirror row_mask:0xf bank_mask:0xf bound_ctrl:1
	v_add_f32_dpp v227, v227, v227 row_bcast:15 row_mask:0xa bank_mask:0xf
	v_add_f32_dpp v228, v228, v228 row_bcast:15 row_mask:0xa bank_mask:0xf
	v_add_f32_dpp v229, v229, v229 row_bcast:15 row_mask:0xa bank_mask:0xf
	v_add_f32_dpp v230, v230, v230 row_bcast:15 row_mask:0xa bank_mask:0xf
	v_add_f32_dpp v227, v227, v227 row_bcast:31 row_mask:0xc bank_mask:0xf
	v_add_f32_dpp v228, v228, v228 row_bcast:31 row_mask:0xc bank_mask:0xf
	v_add_f32_dpp v229, v229, v229 row_bcast:31 row_mask:0xc bank_mask:0xf
	v_add_f32_dpp v230, v230, v230 row_bcast:31 row_mask:0xc bank_mask:0xf
	v_readlane_b32 s0, v227, 63
	v_readlane_b32 s1, v228, 63
	v_readlane_b32 s33, v229, 63
	v_readlane_b32 s41, v230, 63
	v_mov_b32_e32 v231, s0
	v_mov_b32_e32 v234, s33
	v_sqrt_f32_e32 v231, v231
	v_mul_f32_e32 v235, s41, v210
	v_max_f32_e32 v231, 0x2b8cbccc, v231
	v_rcp_f32_e32 v231, v231
	v_cvt_pk_bf16_f32 v235, v235, v235
	v_mul_f32_e32 v213, v213, v231
	v_mul_f32_e32 v233, s1, v231
	v_mul_f32_e32 v217, -1.0, v213
	v_mul_f32_e32 v216, v213, v132
	v_mul_f32_e32 v218, v211, v208
	v_fmac_f32_e32 v218, v233, v217
	ds_write2st64_b32 v222, v217, v218 offset0:0 offset1:1
	v_mul_f32_e32 v219, v216, v212
	v_mul_f32_e32 v220, v215, v212
	ds_write2st64_b32 v222, v211, v219 offset0:2 offset1:3
	ds_write_b32 v222, v220 offset:1024
	ds_write_b32 v223, v210 offset:0
	ds_write_b32 v223, v234 offset:8
	s_bitcmp1_b32 s72, 0
	s_cbranch_scc1 .Lrwq_nobv_0_q
	global_store_short v175, v235, s[6:7]

.Lrwq_nobv_7_q:
	s_add_u32 s14, s14, 0xa4000
	s_addc_u32 s15, s15, 0
	s_cmp_gt_u32 s30, 61
	s_cbranch_scc1 .LBB0_1368
	s_sub_u32 s0, s98, 0x5200
	s_subb_u32 s1, s99, 0
	global_load_short_d16_hi v172, v175, s[0:1] offset:-2048
	global_load_short_d16_hi v173, v175, s[0:1]
	global_load_short_d16_hi v174, v175, s[0:1] offset:2048
	s_add_u32 s0, s0, 0x5200
	s_addc_u32 s1, s1, 0
	global_load_short_d16_hi v100, v175, s[0:1] offset:-2048
	global_load_short_d16_hi v108, v175, s[0:1]
	global_load_short_d16_hi v116, v175, s[0:1] offset:2048
	s_add_u32 s0, s0, 0x5200
	s_addc_u32 s1, s1, 0
	global_load_short_d16_hi v101, v175, s[0:1] offset:-2048
	global_load_short_d16_hi v109, v175, s[0:1]
	global_load_short_d16_hi v117, v175, s[0:1] offset:2048
	s_add_u32 s0, s0, 0x5200
	s_addc_u32 s1, s1, 0
	global_load_short_d16_hi v102, v175, s[0:1] offset:-2048
	global_load_short_d16_hi v110, v175, s[0:1]
	global_load_short_d16_hi v118, v175, s[0:1] offset:2048
	s_add_u32 s0, s0, 0x5200
	s_addc_u32 s1, s1, 0
	global_load_short_d16_hi v103, v175, s[0:1] offset:-2048
	global_load_short_d16_hi v111, v175, s[0:1]
	global_load_short_d16_hi v119, v175, s[0:1] offset:2048
	s_add_u32 s0, s0, 0x5200
	s_addc_u32 s1, s1, 0
	global_load_short_d16_hi v104, v175, s[0:1] offset:-2048
	global_load_short_d16_hi v112, v175, s[0:1]
	global_load_short_d16_hi v120, v175, s[0:1] offset:2048
	s_add_u32 s0, s0, 0x5200
	s_addc_u32 s1, s1, 0
	global_load_short_d16_hi v105, v175, s[0:1] offset:-2048
	global_load_short_d16_hi v113, v175, s[0:1]
	global_load_short_d16_hi v121, v175, s[0:1] offset:2048
	s_add_u32 s0, s0, 0x5200
	s_addc_u32 s1, s1, 0
	global_load_short_d16_hi v106, v175, s[0:1] offset:-2048
	global_load_short_d16_hi v114, v175, s[0:1]
	global_load_short_d16_hi v122, v175, s[0:1] offset:2048
	s_add_u32 s0, s0, 0x5200
	s_addc_u32 s1, s1, 0
	global_load_short_d16_hi v107, v175, s[0:1] offset:-2048
	global_load_short_d16_hi v115, v175, s[0:1]
	global_load_short_d16_hi v123, v175, s[0:1] offset:2048
	s_add_u32 s0, s100, 0x0
	s_addc_u32 s1, s101, 0
	global_load_short_d16_hi v124, v175, s[0:1]
	global_load_short_d16_hi v125, v175, s[0:1] offset:2048
	s_add_u32 s0, s58, 0x0
	s_addc_u32 s1, s59, 0
	global_load_short_d16_hi v132, v175, s[0:1]
	global_load_short_d16_hi v133, v175, s[0:1] offset:2048
	s_add_u32 s0, s100, 0x1000
	s_addc_u32 s1, s101, 0
	global_load_short_d16_hi v126, v175, s[0:1]
	global_load_short_d16_hi v127, v175, s[0:1] offset:2048
	s_add_u32 s0, s58, 0x1000
	s_addc_u32 s1, s59, 0
	global_load_short_d16_hi v134, v175, s[0:1]
	global_load_short_d16_hi v135, v175, s[0:1] offset:2048
	s_add_u32 s0, s100, 0x2000
	s_addc_u32 s1, s101, 0
	global_load_short_d16_hi v128, v175, s[0:1]
	global_load_short_d16_hi v129, v175, s[0:1] offset:2048
	s_add_u32 s0, s58, 0x2000
	s_addc_u32 s1, s59, 0
	global_load_short_d16_hi v136, v175, s[0:1]
	global_load_short_d16_hi v137, v175, s[0:1] offset:2048
	s_add_u32 s0, s100, 0x3000
	s_addc_u32 s1, s101, 0
	global_load_short_d16_hi v130, v175, s[0:1]
	global_load_short_d16_hi v131, v175, s[0:1] offset:2048
	s_add_u32 s0, s58, 0x3000
	s_addc_u32 s1, s59, 0
	global_load_short_d16_hi v138, v175, s[0:1]
	global_load_short_d16_hi v139, v175, s[0:1] offset:2048
	s_add_u32 s98, s98, 0xa4000
	s_addc_u32 s99, s99, 0
	s_add_u32 s100, s100, 0x10000
	s_addc_u32 s101, s101, 0
	s_add_u32 s58, s58, 0x10000
	s_addc_u32 s59, s59, 0
